# speedup vs baseline: 1.0368x; 1.0146x over previous
; __device__ __forceinline__ float sigmoidf_(float x) { return __fdividef(1.f, 1.f + __expf(-x)); }
; #define E_BLK _Pragma("unroll") for(int ai=0;ai<2;++ai) _Pragma("unroll") for(int m=0;m<4;++m) _Pragma("unroll") for(int bj=0;bj<2;++bj) _Pragma("unroll") for(int n=0;n<2;++n)
; __device__ __forceinline__ f32x4 sig4(f32x4 v) { return f32x4{sigmoidf_(v[0]), sigmoidf_(v[1]), sigmoidf_(v[2]), sigmoidf_(v[3])}; }
; template <int EPI, int nN, int lda, int ldb, int K, int ldc>
; __device__ __forceinline__ void gemm_phase(const Params& p, const u16* __restrict__ A, const u16* __restrict__ Bt, u16* C, u16* shm, int wave_s) {
;     ...
;         E_BLK stg_w8(stg, trow + E_R, tcol + E_C, pack4u8(sig4(acc[ai][bj][m][n])));
;         stage_store8(stg, (unsigned char*)p.out + (size_t)brow * 2048 + (pn - 6) * 256, 2048, tid);
.LBB0_504:
	s_andn2_b64 vcc, exec, s[34:35]
	s_cbranch_vccnz .LBB0_506
	v_mul_f32_e32 v128, 0xbfb8aa3b, v120
	v_exp_f32_e32 v128, v128
	v_lshl_or_b32 v137, v131, 8, v133
	v_mul_f32_e32 v138, 0xbfb8aa3b, v121
	v_exp_f32_e32 v138, v138
	v_add_f32_e32 v128, 1.0, v128
	v_add_f32_e32 v138, 1.0, v138
	v_rcp_f32_e32 v128, v128
	v_mul_f32_e32 v148, 0xbfb8aa3b, v122
	v_exp_f32_e32 v148, v148
	s_nop 0
	v_add_f32_e32 v139, 1.0, v148
	v_mul_f32_e32 v149, 0xbfb8aa3b, v123
	v_exp_f32_e32 v149, v149
	v_rcp_f32_e32 v133, v138
	v_add_f32_e32 v148, 1.0, v149
	v_rcp_f32_e32 v134, v139
	v_fma_f32 v128, v128, s82, 0.5
	v_mul_f32_e32 v139, 0xbfb8aa3b, v112
	v_exp_f32_e32 v139, v139
	v_rcp_f32_e32 v138, v148
	v_fma_f32 v133, v133, s82, 0.5
	v_cvt_u32_f32_e32 v128, v128
	v_cvt_u32_f32_e32 v133, v133
	v_fma_f32 v134, v134, s82, 0.5
	v_fma_f32 v138, v138, s82, 0.5
	v_add_f32_e32 v139, 1.0, v139
	v_cvt_u32_f32_sdwa v134, v134 dst_sel:WORD_1 dst_unused:UNUSED_PAD src0_sel:DWORD
	v_cvt_u32_f32_sdwa v138, v138 dst_sel:BYTE_3 dst_unused:UNUSED_PAD src0_sel:DWORD
	v_lshlrev_b32_e32 v136, 4, v145
	v_lshl_or_b32 v128, v133, 8, v128
	v_or3_b32 v128, v128, v134, v138
	v_xad_u32 v133, v135, v136, v137
	v_mul_f32_e32 v138, 0xbfb8aa3b, v113
	ds_write_b32 v133, v128
	v_exp_f32_e32 v138, v138
	s_nop 0
	v_add_f32_e32 v138, 1.0, v138
	v_mul_f32_e32 v149, 0xbfb8aa3b, v114
	v_exp_f32_e32 v149, v149
	v_rcp_f32_e32 v128, v139
	v_add_f32_e32 v148, 1.0, v149
	v_rcp_f32_e32 v134, v138
	v_mul_f32_e32 v150, 0xbfb8aa3b, v115
	v_exp_f32_e32 v150, v150
	s_nop 0
	v_add_f32_e32 v149, 1.0, v150
	v_rcp_f32_e32 v138, v148
	v_fma_f32 v128, v128, s82, 0.5
	v_rcp_f32_e32 v139, v149
	v_fma_f32 v134, v134, s82, 0.5
	v_cvt_u32_f32_e32 v128, v128
	v_cvt_u32_f32_e32 v134, v134
	v_fma_f32 v138, v138, s82, 0.5
	v_fma_f32 v139, v139, s82, 0.5
	v_mul_f32_e32 v148, 0xbfb8aa3b, v124
	v_cvt_u32_f32_sdwa v138, v138 dst_sel:WORD_1 dst_unused:UNUSED_PAD src0_sel:DWORD
	v_cvt_u32_f32_sdwa v139, v139 dst_sel:BYTE_3 dst_unused:UNUSED_PAD src0_sel:DWORD
	v_exp_f32_e32 v148, v148
	v_lshl_or_b32 v128, v134, 8, v128
	v_or_b32_e32 v149, 16, v135
	v_or3_b32 v128, v128, v138, v139
	v_add_f32_e32 v138, 1.0, v148
	v_xad_u32 v134, v149, v136, v137
	v_mul_f32_e32 v151, 0xbfb8aa3b, v125
	v_exp_f32_e32 v151, v151
	s_nop 0
	v_add_f32_e32 v149, 1.0, v151
	v_mul_f32_e32 v150, 0xbfb8aa3b, v126
	v_rcp_f32_e32 v138, v138
	v_exp_f32_e32 v150, v150
	s_nop 0
	v_add_f32_e32 v150, 1.0, v150
	v_mul_f32_e32 v152, 0xbfb8aa3b, v127
	v_exp_f32_e32 v152, v152
	v_rcp_f32_e32 v139, v149
	v_add_f32_e32 v151, 1.0, v152
	v_rcp_f32_e32 v148, v150
	v_fma_f32 v138, v138, s82, 0.5
	v_fma_f32 v139, v139, s82, 0.5
	v_mul_f32_e32 v150, 0xbfb8aa3b, v116
	v_cvt_u32_f32_e32 v138, v138
	v_cvt_u32_f32_e32 v139, v139
	v_exp_f32_e32 v150, v150
	v_rcp_f32_e32 v149, v151
	v_fma_f32 v148, v148, s82, 0.5
	v_fma_f32 v149, v149, s82, 0.5
	v_lshl_or_b32 v138, v139, 8, v138
	v_add_f32_e32 v139, 1.0, v150
	v_cvt_u32_f32_sdwa v148, v148 dst_sel:WORD_1 dst_unused:UNUSED_PAD src0_sel:DWORD
	v_cvt_u32_f32_sdwa v149, v149 dst_sel:BYTE_3 dst_unused:UNUSED_PAD src0_sel:DWORD
	ds_write_b32 v134, v128
	v_or_b32_e32 v128, 0x80, v135
	v_or3_b32 v138, v138, v148, v149
	v_xad_u32 v128, v128, v136, v137
	v_mul_f32_e32 v149, 0xbfb8aa3b, v117
	ds_write_b32 v128, v138
	v_exp_f32_e32 v149, v149
	s_nop 0
	v_add_f32_e32 v149, 1.0, v149
	v_rcp_f32_e32 v138, v139
	v_mul_f32_e32 v151, 0xbfb8aa3b, v118
	v_exp_f32_e32 v151, v151
	s_nop 0
	v_add_f32_e32 v150, 1.0, v151
	v_mul_f32_e32 v152, 0xbfb8aa3b, v119
	v_exp_f32_e32 v152, v152
	v_rcp_f32_e32 v139, v149
	v_add_f32_e32 v151, 1.0, v152
	v_rcp_f32_e32 v148, v150
	v_fma_f32 v138, v138, s82, 0.5
	v_mul_f32_e32 v150, 0xbfb8aa3b, v104
	v_exp_f32_e32 v150, v150
	v_rcp_f32_e32 v149, v151
	v_fma_f32 v139, v139, s82, 0.5
	v_cvt_u32_f32_e32 v138, v138
	v_cvt_u32_f32_e32 v139, v139
	v_fma_f32 v148, v148, s82, 0.5
	v_fma_f32 v149, v149, s82, 0.5
	v_add_f32_e32 v150, 1.0, v150
	v_cvt_u32_f32_sdwa v148, v148 dst_sel:WORD_1 dst_unused:UNUSED_PAD src0_sel:DWORD
	v_cvt_u32_f32_sdwa v149, v149 dst_sel:BYTE_3 dst_unused:UNUSED_PAD src0_sel:DWORD
	v_lshl_or_b32 v138, v139, 8, v138
	v_or3_b32 v138, v138, v148, v149
	v_mul_f32_e32 v149, 0xbfb8aa3b, v105
	v_exp_f32_e32 v149, v149
	s_nop 0
	v_add_f32_e32 v149, 1.0, v149
	v_mul_f32_e32 v152, 0xbfb8aa3b, v106
	v_exp_f32_e32 v152, v152
	v_rcp_f32_e32 v139, v150
	v_add_f32_e32 v151, 1.0, v152
	v_rcp_f32_e32 v148, v149
	v_mul_f32_e32 v153, 0xbfb8aa3b, v107
	v_exp_f32_e32 v153, v153
	s_nop 0
	v_add_f32_e32 v152, 1.0, v153
	v_rcp_f32_e32 v149, v151
	v_fma_f32 v139, v139, s82, 0.5
	v_mul_f32_e32 v151, 0xbfb8aa3b, v96
	v_exp_f32_e32 v151, v151
	v_fma_f32 v148, v148, s82, 0.5
	v_cvt_u32_f32_e32 v139, v139
	v_cvt_u32_f32_e32 v148, v148
	v_add_f32_e32 v151, 1.0, v151
	v_rcp_f32_e32 v150, v152
	v_or_b32_e32 v135, 0x90, v135
	v_fma_f32 v149, v149, s82, 0.5
	v_fma_f32 v150, v150, s82, 0.5
	v_xad_u32 v135, v135, v136, v137
	v_lshl_or_b32 v136, v148, 8, v139
	v_mul_f32_e32 v148, 0xbfb8aa3b, v97
	v_cvt_u32_f32_sdwa v149, v149 dst_sel:WORD_1 dst_unused:UNUSED_PAD src0_sel:DWORD
	v_cvt_u32_f32_sdwa v150, v150 dst_sel:BYTE_3 dst_unused:UNUSED_PAD src0_sel:DWORD
	v_exp_f32_e32 v148, v148
	v_or3_b32 v136, v136, v149, v150
	v_add_f32_e32 v148, 1.0, v148
	v_mul_f32_e32 v152, 0xbfb8aa3b, v98
	v_exp_f32_e32 v152, v152
	v_rcp_f32_e32 v137, v151
	v_add_f32_e32 v149, 1.0, v152
	v_mul_f32_e32 v151, 0xbfb8aa3b, v99
	v_rcp_f32_e32 v139, v148
	v_exp_f32_e32 v151, v151
	s_nop 0
	v_add_f32_e32 v151, 1.0, v151
	v_rcp_f32_e32 v148, v149
	v_fma_f32 v137, v137, s82, 0.5
	v_mul_f32_e32 v150, 0xbfb8aa3b, v108
	v_exp_f32_e32 v150, v150
	v_rcp_f32_e32 v149, v151
; __device__ __forceinline__ float sigmoidf_(float x) { return __fdividef(1.f, 1.f + __expf(-x)); }
; #define E_BLK _Pragma("unroll") for(int ai=0;ai<2;++ai) _Pragma("unroll") for(int m=0;m<4;++m) _Pragma("unroll") for(int bj=0;bj<2;++bj) _Pragma("unroll") for(int n=0;n<2;++n)
; __device__ __forceinline__ f32x4 sig4(f32x4 v) { return f32x4{sigmoidf_(v[0]), sigmoidf_(v[1]), sigmoidf_(v[2]), sigmoidf_(v[3])}; }
; template <int EPI, int nN, int lda, int ldb, int K, int ldc>
; __device__ __forceinline__ void gemm_phase(const Params& p, const u16* __restrict__ A, const u16* __restrict__ Bt, u16* C, u16* shm, int wave_s) {
;     ...
;         E_BLK stg_w8(stg, trow + E_R, tcol + E_C, pack4u8(sig4(acc[ai][bj][m][n])));
;         stage_store8(stg, (unsigned char*)p.out + (size_t)brow * 2048 + (pn - 6) * 256, 2048, tid);
	v_fma_f32 v139, v139, s82, 0.5
	v_cvt_u32_f32_e32 v137, v137
	v_cvt_u32_f32_e32 v139, v139
	v_fma_f32 v148, v148, s82, 0.5
	v_fma_f32 v149, v149, s82, 0.5
	v_cvt_u32_f32_sdwa v148, v148 dst_sel:WORD_1 dst_unused:UNUSED_PAD src0_sel:DWORD
	v_cvt_u32_f32_sdwa v149, v149 dst_sel:BYTE_3 dst_unused:UNUSED_PAD src0_sel:DWORD
	v_add_f32_e32 v150, 1.0, v150
	ds_write_b32 v133, v136 offset:4096
	v_lshl_or_b32 v136, v139, 8, v137
	v_or3_b32 v136, v136, v148, v149
	v_mul_f32_e32 v148, 0xbfb8aa3b, v109
	v_exp_f32_e32 v148, v148
	s_nop 0
	v_add_f32_e32 v148, 1.0, v148
	v_mul_f32_e32 v152, 0xbfb8aa3b, v110
	v_exp_f32_e32 v152, v152
	v_rcp_f32_e32 v137, v150
	v_add_f32_e32 v149, 1.0, v152
	v_mul_f32_e32 v151, 0xbfb8aa3b, v111
	v_rcp_f32_e32 v139, v148
	v_exp_f32_e32 v151, v151
	s_nop 0
	v_add_f32_e32 v151, 1.0, v151
	v_rcp_f32_e32 v148, v149
	v_fma_f32 v137, v137, s82, 0.5
	v_mul_f32_e32 v150, 0xbfb8aa3b, v100
	v_exp_f32_e32 v150, v150
	v_rcp_f32_e32 v149, v151
	v_fma_f32 v139, v139, s82, 0.5
	v_cvt_u32_f32_e32 v137, v137
	v_cvt_u32_f32_e32 v139, v139
	v_fma_f32 v148, v148, s82, 0.5
	v_fma_f32 v149, v149, s82, 0.5
	v_cvt_u32_f32_sdwa v148, v148 dst_sel:WORD_1 dst_unused:UNUSED_PAD src0_sel:DWORD
	v_cvt_u32_f32_sdwa v149, v149 dst_sel:BYTE_3 dst_unused:UNUSED_PAD src0_sel:DWORD
	v_add_f32_e32 v150, 1.0, v150
	ds_write_b32 v134, v136 offset:4096
	v_lshl_or_b32 v136, v139, 8, v137
	v_or3_b32 v136, v136, v148, v149
	v_mul_f32_e32 v148, 0xbfb8aa3b, v101
	v_exp_f32_e32 v148, v148
	s_nop 0
	v_add_f32_e32 v148, 1.0, v148
	v_mul_f32_e32 v152, 0xbfb8aa3b, v102
	v_exp_f32_e32 v152, v152
	v_rcp_f32_e32 v137, v150
	v_add_f32_e32 v149, 1.0, v152
	v_mul_f32_e32 v151, 0xbfb8aa3b, v103
	v_rcp_f32_e32 v139, v148
	v_exp_f32_e32 v151, v151
	s_nop 0
	v_add_f32_e32 v151, 1.0, v151
	v_rcp_f32_e32 v148, v149
	v_fma_f32 v137, v137, s82, 0.5
	v_mul_f32_e32 v150, 0xbfb8aa3b, v84
	v_exp_f32_e32 v150, v150
	v_rcp_f32_e32 v149, v151
	v_fma_f32 v139, v139, s82, 0.5
	v_cvt_u32_f32_e32 v137, v137
	v_cvt_u32_f32_e32 v139, v139
	v_fma_f32 v148, v148, s82, 0.5
	v_fma_f32 v149, v149, s82, 0.5
	v_cvt_u32_f32_sdwa v148, v148 dst_sel:WORD_1 dst_unused:UNUSED_PAD src0_sel:DWORD
	v_cvt_u32_f32_sdwa v149, v149 dst_sel:BYTE_3 dst_unused:UNUSED_PAD src0_sel:DWORD
	v_add_f32_e32 v150, 1.0, v150
	ds_write_b32 v128, v136 offset:4096
	v_lshl_or_b32 v136, v139, 8, v137
	v_or3_b32 v136, v136, v148, v149
	v_mul_f32_e32 v148, 0xbfb8aa3b, v85
	v_exp_f32_e32 v148, v148
	s_nop 0
	v_add_f32_e32 v148, 1.0, v148
	v_mul_f32_e32 v152, 0xbfb8aa3b, v86
	v_exp_f32_e32 v152, v152
	v_rcp_f32_e32 v137, v150
	v_add_f32_e32 v149, 1.0, v152
	v_mul_f32_e32 v151, 0xbfb8aa3b, v87
	v_rcp_f32_e32 v139, v148
	v_exp_f32_e32 v151, v151
	s_nop 0
	v_add_f32_e32 v151, 1.0, v151
	v_rcp_f32_e32 v148, v149
	v_fma_f32 v137, v137, s82, 0.5
	v_mul_f32_e32 v150, 0xbfb8aa3b, v80
	v_exp_f32_e32 v150, v150
	v_fma_f32 v139, v139, s82, 0.5
	v_cvt_u32_f32_e32 v137, v137
	v_cvt_u32_f32_e32 v139, v139
	v_add_f32_e32 v150, 1.0, v150
	v_rcp_f32_e32 v149, v151
	v_fma_f32 v148, v148, s82, 0.5
	v_fma_f32 v149, v149, s82, 0.5
	ds_write2st64_b32 v135, v138, v136 offset1:16
	v_lshl_or_b32 v136, v139, 8, v137
	v_mul_f32_e32 v139, 0xbfb8aa3b, v81
	v_cvt_u32_f32_sdwa v148, v148 dst_sel:WORD_1 dst_unused:UNUSED_PAD src0_sel:DWORD
	v_cvt_u32_f32_sdwa v149, v149 dst_sel:BYTE_3 dst_unused:UNUSED_PAD src0_sel:DWORD
	v_exp_f32_e32 v139, v139
	v_or3_b32 v136, v136, v148, v149
	v_add_f32_e32 v139, 1.0, v139
	v_mul_f32_e32 v151, 0xbfb8aa3b, v82
	v_exp_f32_e32 v151, v151
	v_rcp_f32_e32 v137, v150
	v_add_f32_e32 v148, 1.0, v151
	v_mul_f32_e32 v150, 0xbfb8aa3b, v83
	v_rcp_f32_e32 v138, v139
	v_exp_f32_e32 v150, v150
	s_nop 0
	v_add_f32_e32 v150, 1.0, v150
	v_rcp_f32_e32 v139, v148
	v_fma_f32 v137, v137, s82, 0.5
	v_mul_f32_e32 v149, 0xbfb8aa3b, v92
	v_exp_f32_e32 v149, v149
	v_rcp_f32_e32 v148, v150
	v_fma_f32 v138, v138, s82, 0.5
	v_cvt_u32_f32_e32 v137, v137
	v_cvt_u32_f32_e32 v138, v138
	v_fma_f32 v139, v139, s82, 0.5
	v_fma_f32 v148, v148, s82, 0.5
	v_cvt_u32_f32_sdwa v139, v139 dst_sel:WORD_1 dst_unused:UNUSED_PAD src0_sel:DWORD
	v_cvt_u32_f32_sdwa v148, v148 dst_sel:BYTE_3 dst_unused:UNUSED_PAD src0_sel:DWORD
	v_add_f32_e32 v149, 1.0, v149
	ds_write_b32 v133, v136 offset:8192
	v_lshl_or_b32 v136, v138, 8, v137
	v_or3_b32 v136, v136, v139, v148
	v_mul_f32_e32 v139, 0xbfb8aa3b, v93
	v_exp_f32_e32 v139, v139
	s_nop 0
	v_add_f32_e32 v139, 1.0, v139
	v_mul_f32_e32 v151, 0xbfb8aa3b, v94
	v_exp_f32_e32 v151, v151
	v_rcp_f32_e32 v137, v149
	v_add_f32_e32 v148, 1.0, v151
	v_mul_f32_e32 v150, 0xbfb8aa3b, v95
	v_rcp_f32_e32 v138, v139
	v_exp_f32_e32 v150, v150
	s_nop 0
	v_add_f32_e32 v150, 1.0, v150
	v_rcp_f32_e32 v139, v148
	v_fma_f32 v137, v137, s82, 0.5
	v_mul_f32_e32 v149, 0xbfb8aa3b, v88
	v_exp_f32_e32 v149, v149
	v_rcp_f32_e32 v148, v150
	v_fma_f32 v138, v138, s82, 0.5
	v_cvt_u32_f32_e32 v137, v137
	v_cvt_u32_f32_e32 v138, v138
	v_fma_f32 v139, v139, s82, 0.5
	v_fma_f32 v148, v148, s82, 0.5
	v_cvt_u32_f32_sdwa v139, v139 dst_sel:WORD_1 dst_unused:UNUSED_PAD src0_sel:DWORD
	v_cvt_u32_f32_sdwa v148, v148 dst_sel:BYTE_3 dst_unused:UNUSED_PAD src0_sel:DWORD
	v_add_f32_e32 v149, 1.0, v149
	ds_write_b32 v134, v136 offset:8192
	v_lshl_or_b32 v136, v138, 8, v137
	v_or3_b32 v136, v136, v139, v148
	v_mul_f32_e32 v139, 0xbfb8aa3b, v89
	v_exp_f32_e32 v139, v139
	s_nop 0
	v_add_f32_e32 v139, 1.0, v139
	v_mul_f32_e32 v151, 0xbfb8aa3b, v90
	v_exp_f32_e32 v151, v151
	v_rcp_f32_e32 v137, v149
	v_add_f32_e32 v148, 1.0, v151
	v_mul_f32_e32 v150, 0xbfb8aa3b, v91
	v_rcp_f32_e32 v138, v139
	v_exp_f32_e32 v150, v150
	s_nop 0
	v_add_f32_e32 v150, 1.0, v150
	v_rcp_f32_e32 v139, v148
; __device__ __forceinline__ float sigmoidf_(float x) { return __fdividef(1.f, 1.f + __expf(-x)); }
; #define E_BLK _Pragma("unroll") for(int ai=0;ai<2;++ai) _Pragma("unroll") for(int m=0;m<4;++m) _Pragma("unroll") for(int bj=0;bj<2;++bj) _Pragma("unroll") for(int n=0;n<2;++n)
; __device__ __forceinline__ f32x4 sig4(f32x4 v) { return f32x4{sigmoidf_(v[0]), sigmoidf_(v[1]), sigmoidf_(v[2]), sigmoidf_(v[3])}; }
; template <int EPI, int nN, int lda, int ldb, int K, int ldc>
; __device__ __forceinline__ void gemm_phase(const Params& p, const u16* __restrict__ A, const u16* __restrict__ Bt, u16* C, u16* shm, int wave_s) {
;     ...
;         E_BLK stg_w8(stg, trow + E_R, tcol + E_C, pack4u8(sig4(acc[ai][bj][m][n])));
;         stage_store8(stg, (unsigned char*)p.out + (size_t)brow * 2048 + (pn - 6) * 256, 2048, tid);
	v_fma_f32 v137, v137, s82, 0.5
	v_mul_f32_e32 v149, 0xbfb8aa3b, v60
	v_exp_f32_e32 v149, v149
	v_rcp_f32_e32 v148, v150
	v_fma_f32 v138, v138, s82, 0.5
	v_cvt_u32_f32_e32 v137, v137
	v_cvt_u32_f32_e32 v138, v138
	v_fma_f32 v139, v139, s82, 0.5
	v_fma_f32 v148, v148, s82, 0.5
	v_cvt_u32_f32_sdwa v139, v139 dst_sel:WORD_1 dst_unused:UNUSED_PAD src0_sel:DWORD
	v_cvt_u32_f32_sdwa v148, v148 dst_sel:BYTE_3 dst_unused:UNUSED_PAD src0_sel:DWORD
	v_add_f32_e32 v149, 1.0, v149
	ds_write_b32 v128, v136 offset:8192
	v_lshl_or_b32 v136, v138, 8, v137
	v_or3_b32 v136, v136, v139, v148
	v_mul_f32_e32 v139, 0xbfb8aa3b, v61
	v_exp_f32_e32 v139, v139
	s_nop 0
	v_add_f32_e32 v139, 1.0, v139
	v_mul_f32_e32 v151, 0xbfb8aa3b, v62
	v_exp_f32_e32 v151, v151
	v_rcp_f32_e32 v137, v149
	v_add_f32_e32 v148, 1.0, v151
	v_mul_f32_e32 v150, 0xbfb8aa3b, v63
	v_rcp_f32_e32 v138, v139
	v_exp_f32_e32 v150, v150
	s_nop 0
	v_add_f32_e32 v150, 1.0, v150
	v_rcp_f32_e32 v139, v148
	v_fma_f32 v137, v137, s82, 0.5
	v_mul_f32_e32 v149, 0xbfb8aa3b, v48
	v_exp_f32_e32 v149, v149
	v_rcp_f32_e32 v148, v150
	v_fma_f32 v138, v138, s82, 0.5
	v_cvt_u32_f32_e32 v137, v137
	v_cvt_u32_f32_e32 v138, v138
	v_fma_f32 v139, v139, s82, 0.5
	v_fma_f32 v148, v148, s82, 0.5
	v_cvt_u32_f32_sdwa v139, v139 dst_sel:WORD_1 dst_unused:UNUSED_PAD src0_sel:DWORD
	v_cvt_u32_f32_sdwa v148, v148 dst_sel:BYTE_3 dst_unused:UNUSED_PAD src0_sel:DWORD
	v_add_f32_e32 v149, 1.0, v149
	v_lshl_or_b32 v137, v138, 8, v137
	v_or3_b32 v137, v137, v139, v148
	v_mul_f32_e32 v139, 0xbfb8aa3b, v49
	v_exp_f32_e32 v139, v139
	ds_write_b32 v133, v137 offset:12288
	v_add_f32_e32 v139, 1.0, v139
	v_mul_f32_e32 v151, 0xbfb8aa3b, v50
	v_exp_f32_e32 v151, v151
	v_rcp_f32_e32 v137, v149
	v_add_f32_e32 v148, 1.0, v151
	v_mul_f32_e32 v150, 0xbfb8aa3b, v51
	v_rcp_f32_e32 v138, v139
	v_exp_f32_e32 v150, v150
	s_nop 0
	v_add_f32_e32 v150, 1.0, v150
	v_rcp_f32_e32 v139, v148
	v_fma_f32 v137, v137, s82, 0.5
	v_mul_f32_e32 v149, 0xbfb8aa3b, v76
	v_exp_f32_e32 v149, v149
	v_rcp_f32_e32 v148, v150
	v_fma_f32 v138, v138, s82, 0.5
	v_cvt_u32_f32_e32 v137, v137
	v_cvt_u32_f32_e32 v138, v138
	v_fma_f32 v139, v139, s82, 0.5
	v_fma_f32 v148, v148, s82, 0.5
	v_cvt_u32_f32_sdwa v139, v139 dst_sel:WORD_1 dst_unused:UNUSED_PAD src0_sel:DWORD
	v_cvt_u32_f32_sdwa v148, v148 dst_sel:BYTE_3 dst_unused:UNUSED_PAD src0_sel:DWORD
	v_add_f32_e32 v149, 1.0, v149
	v_lshl_or_b32 v137, v138, 8, v137
	v_or3_b32 v137, v137, v139, v148
	v_mul_f32_e32 v139, 0xbfb8aa3b, v77
	v_exp_f32_e32 v139, v139
	ds_write_b32 v134, v137 offset:12288
	v_add_f32_e32 v139, 1.0, v139
	v_mul_f32_e32 v151, 0xbfb8aa3b, v78
	v_exp_f32_e32 v151, v151
	v_rcp_f32_e32 v137, v149
	v_add_f32_e32 v148, 1.0, v151
	v_mul_f32_e32 v150, 0xbfb8aa3b, v79
	v_rcp_f32_e32 v138, v139
	v_exp_f32_e32 v150, v150
	s_nop 0
	v_add_f32_e32 v150, 1.0, v150
	v_rcp_f32_e32 v139, v148
	v_fma_f32 v137, v137, s82, 0.5
	v_mul_f32_e32 v149, 0xbfb8aa3b, v64
	v_exp_f32_e32 v149, v149
	v_rcp_f32_e32 v148, v150
	v_fma_f32 v138, v138, s82, 0.5
	v_cvt_u32_f32_e32 v137, v137
	v_cvt_u32_f32_e32 v138, v138
	v_fma_f32 v139, v139, s82, 0.5
	v_fma_f32 v148, v148, s82, 0.5
	v_cvt_u32_f32_sdwa v139, v139 dst_sel:WORD_1 dst_unused:UNUSED_PAD src0_sel:DWORD
	v_cvt_u32_f32_sdwa v148, v148 dst_sel:BYTE_3 dst_unused:UNUSED_PAD src0_sel:DWORD
	v_add_f32_e32 v149, 1.0, v149
	v_lshl_or_b32 v137, v138, 8, v137
	v_or3_b32 v137, v137, v139, v148
	v_mul_f32_e32 v139, 0xbfb8aa3b, v65
	v_exp_f32_e32 v139, v139
	ds_write_b32 v128, v137 offset:12288
	v_add_f32_e32 v139, 1.0, v139
	v_mul_f32_e32 v151, 0xbfb8aa3b, v66
	v_exp_f32_e32 v151, v151
	v_rcp_f32_e32 v137, v149
	v_add_f32_e32 v148, 1.0, v151
	v_mul_f32_e32 v150, 0xbfb8aa3b, v67
	v_rcp_f32_e32 v138, v139
	v_exp_f32_e32 v150, v150
	s_nop 0
	v_add_f32_e32 v150, 1.0, v150
	v_rcp_f32_e32 v139, v148
	v_fma_f32 v137, v137, s82, 0.5
	v_mul_f32_e32 v149, 0xbfb8aa3b, v72
	v_exp_f32_e32 v149, v149
	v_rcp_f32_e32 v148, v150
	v_fma_f32 v138, v138, s82, 0.5
	v_cvt_u32_f32_e32 v137, v137
	v_cvt_u32_f32_e32 v138, v138
	v_fma_f32 v139, v139, s82, 0.5
	v_fma_f32 v148, v148, s82, 0.5
	v_add_f32_e32 v149, 1.0, v149
	v_cvt_u32_f32_sdwa v139, v139 dst_sel:WORD_1 dst_unused:UNUSED_PAD src0_sel:DWORD
	v_cvt_u32_f32_sdwa v148, v148 dst_sel:BYTE_3 dst_unused:UNUSED_PAD src0_sel:DWORD
	v_lshl_or_b32 v137, v138, 8, v137
	v_mul_f32_e32 v138, 0xbfb8aa3b, v73
	v_or3_b32 v137, v137, v139, v148
	v_exp_f32_e32 v138, v138
	ds_write2st64_b32 v135, v136, v137 offset0:32 offset1:48
	v_add_f32_e32 v138, 1.0, v138
	v_mul_f32_e32 v150, 0xbfb8aa3b, v74
	v_exp_f32_e32 v150, v150
	v_rcp_f32_e32 v136, v149
	v_add_f32_e32 v139, 1.0, v150
	v_mul_f32_e32 v149, 0xbfb8aa3b, v75
	v_rcp_f32_e32 v137, v138
	v_exp_f32_e32 v149, v149
	s_nop 0
	v_add_f32_e32 v149, 1.0, v149
	v_rcp_f32_e32 v138, v139
	v_fma_f32 v136, v136, s82, 0.5
	v_mul_f32_e32 v148, 0xbfb8aa3b, v56
	v_exp_f32_e32 v148, v148
	v_rcp_f32_e32 v139, v149
	v_fma_f32 v137, v137, s82, 0.5
	v_cvt_u32_f32_e32 v136, v136
	v_cvt_u32_f32_e32 v137, v137
	v_fma_f32 v138, v138, s82, 0.5
	v_fma_f32 v139, v139, s82, 0.5
	v_cvt_u32_f32_sdwa v138, v138 dst_sel:WORD_1 dst_unused:UNUSED_PAD src0_sel:DWORD
	v_cvt_u32_f32_sdwa v139, v139 dst_sel:BYTE_3 dst_unused:UNUSED_PAD src0_sel:DWORD
	v_add_f32_e32 v148, 1.0, v148
	v_lshl_or_b32 v136, v137, 8, v136
	v_or3_b32 v136, v136, v138, v139
	v_mul_f32_e32 v138, 0xbfb8aa3b, v57
	v_exp_f32_e32 v138, v138
	ds_write_b32 v133, v136 offset:32768
	v_add_f32_e32 v138, 1.0, v138
	v_mul_f32_e32 v150, 0xbfb8aa3b, v58
	v_exp_f32_e32 v150, v150
	v_rcp_f32_e32 v136, v148
	v_add_f32_e32 v139, 1.0, v150
	v_mul_f32_e32 v149, 0xbfb8aa3b, v59
	v_rcp_f32_e32 v137, v138
; __device__ __forceinline__ float sigmoidf_(float x) { return __fdividef(1.f, 1.f + __expf(-x)); }
; #define E_BLK _Pragma("unroll") for(int ai=0;ai<2;++ai) _Pragma("unroll") for(int m=0;m<4;++m) _Pragma("unroll") for(int bj=0;bj<2;++bj) _Pragma("unroll") for(int n=0;n<2;++n)
; __device__ __forceinline__ f32x4 sig4(f32x4 v) { return f32x4{sigmoidf_(v[0]), sigmoidf_(v[1]), sigmoidf_(v[2]), sigmoidf_(v[3])}; }
; template <int EPI, int nN, int lda, int ldb, int K, int ldc>
; __device__ __forceinline__ void gemm_phase(const Params& p, const u16* __restrict__ A, const u16* __restrict__ Bt, u16* C, u16* shm, int wave_s) {
;     ...
;         E_BLK stg_w8(stg, trow + E_R, tcol + E_C, pack4u8(sig4(acc[ai][bj][m][n])));
;         stage_store8(stg, (unsigned char*)p.out + (size_t)brow * 2048 + (pn - 6) * 256, 2048, tid);
	v_exp_f32_e32 v149, v149
	s_nop 0
	v_add_f32_e32 v149, 1.0, v149
	v_rcp_f32_e32 v138, v139
	v_fma_f32 v136, v136, s82, 0.5
	v_mul_f32_e32 v148, 0xbfb8aa3b, v68
	v_exp_f32_e32 v148, v148
	v_rcp_f32_e32 v139, v149
	v_fma_f32 v137, v137, s82, 0.5
	v_cvt_u32_f32_e32 v136, v136
	v_cvt_u32_f32_e32 v137, v137
	v_fma_f32 v138, v138, s82, 0.5
	v_fma_f32 v139, v139, s82, 0.5
	v_cvt_u32_f32_sdwa v138, v138 dst_sel:WORD_1 dst_unused:UNUSED_PAD src0_sel:DWORD
	v_cvt_u32_f32_sdwa v139, v139 dst_sel:BYTE_3 dst_unused:UNUSED_PAD src0_sel:DWORD
	v_add_f32_e32 v148, 1.0, v148
	v_lshl_or_b32 v136, v137, 8, v136
	v_or3_b32 v136, v136, v138, v139
	v_mul_f32_e32 v138, 0xbfb8aa3b, v69
	v_exp_f32_e32 v138, v138
	ds_write_b32 v134, v136 offset:32768
	v_add_f32_e32 v138, 1.0, v138
	v_mul_f32_e32 v150, 0xbfb8aa3b, v70
	v_exp_f32_e32 v150, v150
	v_rcp_f32_e32 v136, v148
	v_add_f32_e32 v139, 1.0, v150
	v_mul_f32_e32 v149, 0xbfb8aa3b, v71
	v_rcp_f32_e32 v137, v138
	v_exp_f32_e32 v149, v149
	s_nop 0
	v_add_f32_e32 v149, 1.0, v149
	v_rcp_f32_e32 v138, v139
	v_fma_f32 v136, v136, s82, 0.5
	v_mul_f32_e32 v148, 0xbfb8aa3b, v52
	v_exp_f32_e32 v148, v148
	v_rcp_f32_e32 v139, v149
	v_fma_f32 v137, v137, s82, 0.5
	v_cvt_u32_f32_e32 v136, v136
	v_cvt_u32_f32_e32 v137, v137
	v_fma_f32 v138, v138, s82, 0.5
	v_fma_f32 v139, v139, s82, 0.5
	v_cvt_u32_f32_sdwa v138, v138 dst_sel:WORD_1 dst_unused:UNUSED_PAD src0_sel:DWORD
	v_cvt_u32_f32_sdwa v139, v139 dst_sel:BYTE_3 dst_unused:UNUSED_PAD src0_sel:DWORD
	v_add_f32_e32 v148, 1.0, v148
	v_lshl_or_b32 v136, v137, 8, v136
	v_or3_b32 v136, v136, v138, v139
	v_mul_f32_e32 v138, 0xbfb8aa3b, v53
	v_exp_f32_e32 v138, v138
	ds_write_b32 v128, v136 offset:32768
	v_add_f32_e32 v138, 1.0, v138
	v_mul_f32_e32 v150, 0xbfb8aa3b, v54
	v_exp_f32_e32 v150, v150
	v_rcp_f32_e32 v136, v148
	v_add_f32_e32 v139, 1.0, v150
	v_mul_f32_e32 v149, 0xbfb8aa3b, v55
	v_rcp_f32_e32 v137, v138
	v_exp_f32_e32 v149, v149
	s_nop 0
	v_add_f32_e32 v149, 1.0, v149
	v_rcp_f32_e32 v138, v139
	v_fma_f32 v136, v136, s82, 0.5
	v_mul_f32_e32 v148, 0xbfb8aa3b, v44
	v_exp_f32_e32 v148, v148
	v_rcp_f32_e32 v139, v149
	v_fma_f32 v137, v137, s82, 0.5
	v_cvt_u32_f32_e32 v136, v136
	v_add_f32_e32 v148, 1.0, v148
	v_cvt_u32_f32_e32 v137, v137
	v_mul_f32_e32 v152, 0xbfb8aa3b, v45
	v_exp_f32_e32 v152, v152
	v_lshl_or_b32 v136, v137, 8, v136
	v_add_f32_e32 v149, 1.0, v152
	v_mul_f32_e32 v151, 0xbfb8aa3b, v46
	v_rcp_f32_e32 v137, v148
	v_exp_f32_e32 v151, v151
	s_nop 0
	v_add_f32_e32 v151, 1.0, v151
	v_rcp_f32_e32 v148, v149
	v_mul_f32_e32 v153, 0xbfb8aa3b, v47
	v_exp_f32_e32 v153, v153
	s_nop 0
	v_add_f32_e32 v152, 1.0, v153
	v_rcp_f32_e32 v149, v151
	v_fma_f32 v137, v137, s82, 0.5
	v_mul_f32_e32 v151, 0xbfb8aa3b, v36
	v_exp_f32_e32 v151, v151
	v_fma_f32 v148, v148, s82, 0.5
	v_cvt_u32_f32_e32 v137, v137
	v_cvt_u32_f32_e32 v148, v148
	v_add_f32_e32 v151, 1.0, v151
	v_fma_f32 v138, v138, s82, 0.5
	v_fma_f32 v139, v139, s82, 0.5
	v_rcp_f32_e32 v150, v152
	v_cvt_u32_f32_sdwa v138, v138 dst_sel:WORD_1 dst_unused:UNUSED_PAD src0_sel:DWORD
	v_cvt_u32_f32_sdwa v139, v139 dst_sel:BYTE_3 dst_unused:UNUSED_PAD src0_sel:DWORD
	v_fma_f32 v149, v149, s82, 0.5
	v_fma_f32 v150, v150, s82, 0.5
	v_lshl_or_b32 v137, v148, 8, v137
	v_mul_f32_e32 v148, 0xbfb8aa3b, v37
	v_cvt_u32_f32_sdwa v149, v149 dst_sel:WORD_1 dst_unused:UNUSED_PAD src0_sel:DWORD
	v_cvt_u32_f32_sdwa v150, v150 dst_sel:BYTE_3 dst_unused:UNUSED_PAD src0_sel:DWORD
	v_exp_f32_e32 v148, v148
	v_or3_b32 v136, v136, v138, v139
	v_or3_b32 v137, v137, v149, v150
	v_add_f32_e32 v148, 1.0, v148
	v_mul_f32_e32 v152, 0xbfb8aa3b, v38
	v_exp_f32_e32 v152, v152
	v_rcp_f32_e32 v138, v151
	v_add_f32_e32 v149, 1.0, v152
	v_mul_f32_e32 v151, 0xbfb8aa3b, v39
	v_rcp_f32_e32 v139, v148
	v_exp_f32_e32 v151, v151
	s_nop 0
	v_add_f32_e32 v151, 1.0, v151
	v_rcp_f32_e32 v148, v149
	v_fma_f32 v138, v138, s82, 0.5
	v_mul_f32_e32 v150, 0xbfb8aa3b, v40
	v_exp_f32_e32 v150, v150
	v_rcp_f32_e32 v149, v151
	v_fma_f32 v139, v139, s82, 0.5
	v_cvt_u32_f32_e32 v138, v138
	v_cvt_u32_f32_e32 v139, v139
	v_fma_f32 v148, v148, s82, 0.5
	v_fma_f32 v149, v149, s82, 0.5
	v_cvt_u32_f32_sdwa v148, v148 dst_sel:WORD_1 dst_unused:UNUSED_PAD src0_sel:DWORD
	v_cvt_u32_f32_sdwa v149, v149 dst_sel:BYTE_3 dst_unused:UNUSED_PAD src0_sel:DWORD
	v_add_f32_e32 v150, 1.0, v150
	ds_write_b32 v133, v137 offset:36864
	v_lshl_or_b32 v137, v139, 8, v138
	v_or3_b32 v137, v137, v148, v149
	v_mul_f32_e32 v148, 0xbfb8aa3b, v41
	v_exp_f32_e32 v148, v148
	s_nop 0
	v_add_f32_e32 v148, 1.0, v148
	v_mul_f32_e32 v152, 0xbfb8aa3b, v42
	v_exp_f32_e32 v152, v152
	v_rcp_f32_e32 v138, v150
	v_add_f32_e32 v149, 1.0, v152
	v_mul_f32_e32 v151, 0xbfb8aa3b, v43
	v_rcp_f32_e32 v139, v148
	v_exp_f32_e32 v151, v151
	s_nop 0
	v_add_f32_e32 v151, 1.0, v151
	v_rcp_f32_e32 v148, v149
	v_fma_f32 v138, v138, s82, 0.5
	v_mul_f32_e32 v150, 0xbfb8aa3b, v32
	v_exp_f32_e32 v150, v150
	v_rcp_f32_e32 v149, v151
	v_fma_f32 v139, v139, s82, 0.5
	v_cvt_u32_f32_e32 v138, v138
	v_cvt_u32_f32_e32 v139, v139
	v_fma_f32 v148, v148, s82, 0.5
	v_fma_f32 v149, v149, s82, 0.5
	v_cvt_u32_f32_sdwa v148, v148 dst_sel:WORD_1 dst_unused:UNUSED_PAD src0_sel:DWORD
	v_cvt_u32_f32_sdwa v149, v149 dst_sel:BYTE_3 dst_unused:UNUSED_PAD src0_sel:DWORD
	v_add_f32_e32 v150, 1.0, v150
	ds_write_b32 v134, v137 offset:36864
	v_lshl_or_b32 v137, v139, 8, v138
	v_or3_b32 v137, v137, v148, v149
	v_mul_f32_e32 v148, 0xbfb8aa3b, v33
	v_exp_f32_e32 v148, v148
	s_nop 0
	v_add_f32_e32 v148, 1.0, v148
	v_mul_f32_e32 v152, 0xbfb8aa3b, v34
	v_exp_f32_e32 v152, v152
	v_rcp_f32_e32 v138, v150
	v_add_f32_e32 v149, 1.0, v152
	v_mul_f32_e32 v151, 0xbfb8aa3b, v35
	v_rcp_f32_e32 v139, v148
; __device__ __forceinline__ float sigmoidf_(float x) { return __fdividef(1.f, 1.f + __expf(-x)); }
; #define E_BLK _Pragma("unroll") for(int ai=0;ai<2;++ai) _Pragma("unroll") for(int m=0;m<4;++m) _Pragma("unroll") for(int bj=0;bj<2;++bj) _Pragma("unroll") for(int n=0;n<2;++n)
; __device__ __forceinline__ f32x4 sig4(f32x4 v) { return f32x4{sigmoidf_(v[0]), sigmoidf_(v[1]), sigmoidf_(v[2]), sigmoidf_(v[3])}; }
; template <int EPI, int nN, int lda, int ldb, int K, int ldc>
; __device__ __forceinline__ void gemm_phase(const Params& p, const u16* __restrict__ A, const u16* __restrict__ Bt, u16* C, u16* shm, int wave_s) {
;     ...
;         E_BLK stg_w8(stg, trow + E_R, tcol + E_C, pack4u8(sig4(acc[ai][bj][m][n])));
;         stage_store8(stg, (unsigned char*)p.out + (size_t)brow * 2048 + (pn - 6) * 256, 2048, tid);
	v_exp_f32_e32 v151, v151
	s_nop 0
	v_add_f32_e32 v151, 1.0, v151
	v_rcp_f32_e32 v148, v149
	v_fma_f32 v138, v138, s82, 0.5
	v_mul_f32_e32 v150, 0xbfb8aa3b, v28
	v_exp_f32_e32 v150, v150
	v_rcp_f32_e32 v149, v151
	v_fma_f32 v139, v139, s82, 0.5
	v_cvt_u32_f32_e32 v138, v138
	v_cvt_u32_f32_e32 v139, v139
	v_fma_f32 v148, v148, s82, 0.5
	v_fma_f32 v149, v149, s82, 0.5
	v_cvt_u32_f32_sdwa v148, v148 dst_sel:WORD_1 dst_unused:UNUSED_PAD src0_sel:DWORD
	v_cvt_u32_f32_sdwa v149, v149 dst_sel:BYTE_3 dst_unused:UNUSED_PAD src0_sel:DWORD
	v_add_f32_e32 v150, 1.0, v150
	ds_write_b32 v128, v137 offset:36864
	v_lshl_or_b32 v137, v139, 8, v138
	v_or3_b32 v137, v137, v148, v149
	v_mul_f32_e32 v148, 0xbfb8aa3b, v29
	v_exp_f32_e32 v148, v148
	s_nop 0
	v_add_f32_e32 v148, 1.0, v148
	v_mul_f32_e32 v152, 0xbfb8aa3b, v30
	v_exp_f32_e32 v152, v152
	v_rcp_f32_e32 v138, v150
	v_add_f32_e32 v149, 1.0, v152
	v_mul_f32_e32 v151, 0xbfb8aa3b, v31
	v_rcp_f32_e32 v139, v148
	v_exp_f32_e32 v151, v151
	s_nop 0
	v_add_f32_e32 v151, 1.0, v151
	v_rcp_f32_e32 v148, v149
	v_fma_f32 v138, v138, s82, 0.5
	v_mul_f32_e32 v150, 0xbfb8aa3b, v20
	v_exp_f32_e32 v150, v150
	v_fma_f32 v139, v139, s82, 0.5
	v_cvt_u32_f32_e32 v138, v138
	v_cvt_u32_f32_e32 v139, v139
	v_add_f32_e32 v150, 1.0, v150
	v_rcp_f32_e32 v149, v151
	v_fma_f32 v148, v148, s82, 0.5
	v_fma_f32 v149, v149, s82, 0.5
	ds_write2st64_b32 v135, v136, v137 offset0:128 offset1:144
	v_lshl_or_b32 v136, v139, 8, v138
	v_mul_f32_e32 v139, 0xbfb8aa3b, v21
	v_cvt_u32_f32_sdwa v148, v148 dst_sel:WORD_1 dst_unused:UNUSED_PAD src0_sel:DWORD
	v_cvt_u32_f32_sdwa v149, v149 dst_sel:BYTE_3 dst_unused:UNUSED_PAD src0_sel:DWORD
	v_exp_f32_e32 v139, v139
	v_or3_b32 v136, v136, v148, v149
	v_add_f32_e32 v139, 1.0, v139
	v_mul_f32_e32 v151, 0xbfb8aa3b, v22
	v_exp_f32_e32 v151, v151
	v_rcp_f32_e32 v137, v150
	v_add_f32_e32 v148, 1.0, v151
	v_mul_f32_e32 v150, 0xbfb8aa3b, v23
	v_rcp_f32_e32 v138, v139
	v_exp_f32_e32 v150, v150
	s_nop 0
	v_add_f32_e32 v150, 1.0, v150
	v_rcp_f32_e32 v139, v148
	v_fma_f32 v137, v137, s82, 0.5
	v_mul_f32_e32 v149, 0xbfb8aa3b, v24
	v_exp_f32_e32 v149, v149
	v_rcp_f32_e32 v148, v150
	v_fma_f32 v138, v138, s82, 0.5
	v_cvt_u32_f32_e32 v137, v137
	v_cvt_u32_f32_e32 v138, v138
	v_fma_f32 v139, v139, s82, 0.5
	v_fma_f32 v148, v148, s82, 0.5
	v_cvt_u32_f32_sdwa v139, v139 dst_sel:WORD_1 dst_unused:UNUSED_PAD src0_sel:DWORD
	v_cvt_u32_f32_sdwa v148, v148 dst_sel:BYTE_3 dst_unused:UNUSED_PAD src0_sel:DWORD
	v_add_f32_e32 v149, 1.0, v149
	ds_write_b32 v133, v136 offset:40960
	v_lshl_or_b32 v136, v138, 8, v137
	v_or3_b32 v136, v136, v139, v148
	v_mul_f32_e32 v139, 0xbfb8aa3b, v25
	v_exp_f32_e32 v139, v139
	s_nop 0
	v_add_f32_e32 v139, 1.0, v139
	v_mul_f32_e32 v151, 0xbfb8aa3b, v26
	v_exp_f32_e32 v151, v151
	v_rcp_f32_e32 v137, v149
	v_add_f32_e32 v148, 1.0, v151
	v_mul_f32_e32 v150, 0xbfb8aa3b, v27
	v_rcp_f32_e32 v138, v139
	v_exp_f32_e32 v150, v150
	s_nop 0
	v_add_f32_e32 v150, 1.0, v150
	v_rcp_f32_e32 v139, v148
	v_fma_f32 v137, v137, s82, 0.5
	v_mul_f32_e32 v149, 0xbfb8aa3b, v16
	v_exp_f32_e32 v149, v149
	v_rcp_f32_e32 v148, v150
	v_fma_f32 v138, v138, s82, 0.5
	v_cvt_u32_f32_e32 v137, v137
	v_cvt_u32_f32_e32 v138, v138
	v_fma_f32 v139, v139, s82, 0.5
	v_fma_f32 v148, v148, s82, 0.5
	v_cvt_u32_f32_sdwa v139, v139 dst_sel:WORD_1 dst_unused:UNUSED_PAD src0_sel:DWORD
	v_cvt_u32_f32_sdwa v148, v148 dst_sel:BYTE_3 dst_unused:UNUSED_PAD src0_sel:DWORD
	v_add_f32_e32 v149, 1.0, v149
	ds_write_b32 v134, v136 offset:40960
	v_lshl_or_b32 v136, v138, 8, v137
	v_or3_b32 v136, v136, v139, v148
	v_mul_f32_e32 v139, 0xbfb8aa3b, v17
	v_exp_f32_e32 v139, v139
	s_nop 0
	v_add_f32_e32 v139, 1.0, v139
	v_mul_f32_e32 v151, 0xbfb8aa3b, v18
	v_exp_f32_e32 v151, v151
	v_rcp_f32_e32 v137, v149
	v_add_f32_e32 v148, 1.0, v151
	v_mul_f32_e32 v150, 0xbfb8aa3b, v19
	v_rcp_f32_e32 v138, v139
	v_exp_f32_e32 v150, v150
	s_nop 0
	v_add_f32_e32 v150, 1.0, v150
	v_rcp_f32_e32 v139, v148
	v_fma_f32 v137, v137, s82, 0.5
	v_mul_f32_e32 v149, 0xbfb8aa3b, v12
	v_exp_f32_e32 v149, v149
	v_rcp_f32_e32 v148, v150
	v_fma_f32 v138, v138, s82, 0.5
	v_cvt_u32_f32_e32 v137, v137
	v_cvt_u32_f32_e32 v138, v138
	v_fma_f32 v139, v139, s82, 0.5
	v_fma_f32 v148, v148, s82, 0.5
	v_cvt_u32_f32_sdwa v139, v139 dst_sel:WORD_1 dst_unused:UNUSED_PAD src0_sel:DWORD
	v_cvt_u32_f32_sdwa v148, v148 dst_sel:BYTE_3 dst_unused:UNUSED_PAD src0_sel:DWORD
	v_add_f32_e32 v149, 1.0, v149
	ds_write_b32 v128, v136 offset:40960
	v_lshl_or_b32 v136, v138, 8, v137
	v_or3_b32 v136, v136, v139, v148
	v_mul_f32_e32 v139, 0xbfb8aa3b, v13
	v_exp_f32_e32 v139, v139
	s_nop 0
	v_add_f32_e32 v139, 1.0, v139
	v_mul_f32_e32 v151, 0xbfb8aa3b, v14
	v_exp_f32_e32 v151, v151
	v_rcp_f32_e32 v137, v149
	v_add_f32_e32 v148, 1.0, v151
	v_mul_f32_e32 v150, 0xbfb8aa3b, v15
	v_rcp_f32_e32 v138, v139
	v_exp_f32_e32 v150, v150
	s_nop 0
	v_add_f32_e32 v150, 1.0, v150
	v_rcp_f32_e32 v139, v148
	v_fma_f32 v137, v137, s82, 0.5
	v_mul_f32_e32 v149, 0xbfb8aa3b, v4
	v_exp_f32_e32 v149, v149
	v_rcp_f32_e32 v148, v150
	v_fma_f32 v138, v138, s82, 0.5
	v_cvt_u32_f32_e32 v137, v137
	v_cvt_u32_f32_e32 v138, v138
	v_fma_f32 v139, v139, s82, 0.5
; __device__ __forceinline__ void stage_store8(const char* stg, unsigned char* dst, int ld, int tid) {
;   __syncthreads();
;   const int j = tid & 15, r0 = tid >> 4;
; #pragma unroll
;   for (int i = 0; i < 8; ++i) { const int r = i * 32 + r0;
;     __builtin_nontemporal_store(*reinterpret_cast<const u32x4*>(stg + r * 256 + ((j ^ (r & 15)) << 4)), reinterpret_cast<u32x4*>(dst + (unsigned)(r * ld + j * 16))); }
;   __syncthreads();
	v_fma_f32 v148, v148, s82, 0.5
	v_add_f32_e32 v149, 1.0, v149
	v_cvt_u32_f32_sdwa v139, v139 dst_sel:WORD_1 dst_unused:UNUSED_PAD src0_sel:DWORD
	v_cvt_u32_f32_sdwa v148, v148 dst_sel:BYTE_3 dst_unused:UNUSED_PAD src0_sel:DWORD
	v_lshl_or_b32 v137, v138, 8, v137
	v_mul_f32_e32 v138, 0xbfb8aa3b, v5
	v_or3_b32 v137, v137, v139, v148
	v_exp_f32_e32 v138, v138
	ds_write_b32 v133, v137 offset:45056
	v_add_f32_e32 v138, 1.0, v138
	v_mul_f32_e32 v150, 0xbfb8aa3b, v6
	v_exp_f32_e32 v150, v150
	v_rcp_f32_e32 v133, v149
	v_add_f32_e32 v139, 1.0, v150
	v_mul_f32_e32 v149, 0xbfb8aa3b, v7
	v_rcp_f32_e32 v137, v138
	v_exp_f32_e32 v149, v149
	s_nop 0
	v_add_f32_e32 v149, 1.0, v149
	v_rcp_f32_e32 v138, v139
	v_fma_f32 v133, v133, s82, 0.5
	v_mul_f32_e32 v148, 0xbfb8aa3b, v8
	v_exp_f32_e32 v148, v148
	v_rcp_f32_e32 v139, v149
	v_fma_f32 v137, v137, s82, 0.5
	v_cvt_u32_f32_e32 v133, v133
	v_cvt_u32_f32_e32 v137, v137
	v_fma_f32 v138, v138, s82, 0.5
	v_fma_f32 v139, v139, s82, 0.5
	v_add_f32_e32 v148, 1.0, v148
	v_cvt_u32_f32_sdwa v138, v138 dst_sel:WORD_1 dst_unused:UNUSED_PAD src0_sel:DWORD
	v_cvt_u32_f32_sdwa v139, v139 dst_sel:BYTE_3 dst_unused:UNUSED_PAD src0_sel:DWORD
	v_lshl_or_b32 v133, v137, 8, v133
	v_mul_f32_e32 v137, 0xbfb8aa3b, v9
	v_or3_b32 v133, v133, v138, v139
	v_exp_f32_e32 v137, v137
	ds_write_b32 v134, v133 offset:45056
	v_add_f32_e32 v137, 1.0, v137
	v_mul_f32_e32 v149, 0xbfb8aa3b, v10
	v_exp_f32_e32 v149, v149
	v_rcp_f32_e32 v133, v148
	v_add_f32_e32 v138, 1.0, v149
	v_mul_f32_e32 v148, 0xbfb8aa3b, v11
	v_rcp_f32_e32 v134, v137
	v_exp_f32_e32 v148, v148
	s_nop 0
	v_add_f32_e32 v148, 1.0, v148
	v_rcp_f32_e32 v137, v138
	v_fma_f32 v133, v133, s82, 0.5
	v_mul_f32_e32 v139, 0xbfb8aa3b, v0
	v_exp_f32_e32 v139, v139
	v_rcp_f32_e32 v138, v148
	v_fma_f32 v134, v134, s82, 0.5
	v_cvt_u32_f32_e32 v133, v133
	v_add_f32_e32 v139, 1.0, v139
	v_cvt_u32_f32_e32 v134, v134
	v_mul_f32_e32 v151, 0xbfb8aa3b, v1
	v_exp_f32_e32 v151, v151
	v_lshl_or_b32 v133, v134, 8, v133
	v_add_f32_e32 v148, 1.0, v151
	v_mul_f32_e32 v150, 0xbfb8aa3b, v2
	v_rcp_f32_e32 v134, v139
	v_exp_f32_e32 v150, v150
	s_nop 0
	v_add_f32_e32 v150, 1.0, v150
	v_rcp_f32_e32 v139, v148
	v_mul_f32_e32 v152, 0xbfb8aa3b, v3
	v_exp_f32_e32 v152, v152
	s_nop 0
	v_add_f32_e32 v151, 1.0, v152
	v_rcp_f32_e32 v148, v150
	v_fma_f32 v137, v137, s82, 0.5
	v_div_scale_f32 v149, vcc, 1.0, v151, 1.0
	v_fma_f32 v138, v138, s82, 0.5
	v_cvt_u32_f32_sdwa v137, v137 dst_sel:WORD_1 dst_unused:UNUSED_PAD src0_sel:DWORD
	v_cvt_u32_f32_sdwa v138, v138 dst_sel:BYTE_3 dst_unused:UNUSED_PAD src0_sel:DWORD
	v_rcp_f32_e32 v149, v151
	v_fma_f32 v134, v134, s82, 0.5
	v_fma_f32 v139, v139, s82, 0.5
	v_cvt_u32_f32_e32 v134, v134
	v_cvt_u32_f32_e32 v139, v139
	v_fma_f32 v148, v148, s82, 0.5
	v_fma_f32 v149, v149, s82, 0.5
	v_cvt_u32_f32_sdwa v148, v148 dst_sel:WORD_1 dst_unused:UNUSED_PAD src0_sel:DWORD
	v_cvt_u32_f32_sdwa v149, v149 dst_sel:BYTE_3 dst_unused:UNUSED_PAD src0_sel:DWORD
	v_or3_b32 v133, v133, v137, v138
	ds_write_b32 v128, v133 offset:45056
	v_lshl_or_b32 v128, v139, 8, v134
	v_or3_b32 v128, v128, v148, v149
	ds_write2st64_b32 v135, v136, v128 offset0:160 offset1:176
	v_ashrrev_i32_e32 v128, 4, v144
	v_xor_b32_e32 v133, v128, v143
	v_lshlrev_b32_e32 v133, 4, v133
	v_and_b32_e32 v133, 0xf0, v133
	v_lshl_or_b32 v134, v128, 8, v133
	s_waitcnt vmcnt(0) lgkmcnt(0)
	s_barrier
	ds_read_b128 v[134:137], v134
	s_add_u32 s5, s24, s6
	s_addc_u32 s7, s25, s7
	s_add_u32 s6, s5, s4
	v_and_b32_e32 v138, 0xf0, v147
	v_add_u32_e32 v147, 32, v128
	s_addc_u32 s7, s7, 0
	v_lshl_or_b32 v139, v128, 11, v138
	v_lshl_or_b32 v148, v147, 8, v133
	ds_read_b128 v[148:151], v148
	s_waitcnt lgkmcnt(1)
	global_store_dwordx4 v139, v[134:137], s[6:7] offset:-1536 nt
	v_lshl_or_b32 v139, v147, 11, v138
	v_add_u32_e32 v147, 64, v128
	v_lshl_or_b32 v134, v147, 8, v133
	v_add_u32_e32 v156, 0x60, v128
	ds_read_b128 v[134:137], v134
	v_lshl_or_b32 v152, v156, 8, v133
	ds_read_b128 v[152:155], v152
	s_waitcnt lgkmcnt(2)
	global_store_dwordx4 v139, v[148:151], s[6:7] offset:-1536 nt
	v_lshl_or_b32 v139, v147, 11, v138
	v_add_u32_e32 v147, 0xa0, v128
	v_lshl_or_b32 v148, v147, 8, v133
	ds_read_b128 v[148:151], v148
	s_waitcnt lgkmcnt(2)
	global_store_dwordx4 v139, v[134:137], s[6:7] offset:-1536 nt
	v_add_u32_e32 v139, 0x80, v128
	s_nop 0
	v_lshl_or_b32 v134, v156, 11, v138
	s_waitcnt lgkmcnt(1)
	global_store_dwordx4 v134, v[152:155], s[6:7] offset:-1536 nt
	v_lshl_or_b32 v134, v139, 8, v133
	ds_read_b128 v[134:137], v134
	v_lshl_or_b32 v139, v139, 11, v138
	s_waitcnt lgkmcnt(0)
	global_store_dwordx4 v139, v[134:137], s[6:7] offset:-1536 nt
	v_lshl_or_b32 v139, v147, 11, v138
	v_add_u32_e32 v147, 0xc0, v128
	v_add_u32_e32 v128, 0xe0, v128
	v_lshl_or_b32 v134, v147, 8, v133
	v_lshl_or_b32 v133, v128, 8, v133
	ds_read_b128 v[134:137], v134
	ds_read_b128 v[152:155], v133
	v_lshl_or_b32 v133, v147, 11, v138
	v_lshl_or_b32 v128, v128, 11, v138
	global_store_dwordx4 v139, v[148:151], s[6:7] offset:-1536 nt
	s_waitcnt lgkmcnt(1)
	global_store_dwordx4 v133, v[134:137], s[6:7] offset:-1536 nt
	s_waitcnt lgkmcnt(0)
	global_store_dwordx4 v128, v[152:155], s[6:7] offset:-1536 nt
	s_barrier

; __device__ __forceinline__ float bflo(unsigned w) { return __uint_as_float(w << 16); }
; __device__ __forceinline__ float bfhi(unsigned w) { return __uint_as_float(w & 0xffff0000u); }
; __device__ __forceinline__ float sigmoidf_(float x) { return __fdividef(1.f, 1.f + __expf(-x)); }
; __device__ __forceinline__ u32x2 pack4(f32x4 v) { return u32x2{cvtpk(v[0], v[1]), cvtpk(v[2], v[3])}; }
; __device__ __forceinline__ f32x4 unpack4(u32x2 w) { return f32x4{bflo(w[0]), bfhi(w[0]), bflo(w[1]), bfhi(w[1])}; }
; __device__ __forceinline__ f32x4 sig4(f32x4 v) { return f32x4{sigmoidf_(v[0]), sigmoidf_(v[1]), sigmoidf_(v[2]), sigmoidf_(v[3])}; }
; template <int EPI, int nN, int lda, int ldb, int K, int ldc>
; __device__ __forceinline__ void gemm_phase(const Params& p, const u16* __restrict__ A, const u16* __restrict__ Bt, u16* C, u16* shm, int wave_s) {
;     ...
;       } else if (pn < 6) {
;         _Pragma("unroll") for (int ai = 0; ai < 2; ++ai) _Pragma("unroll") for (int m = 0; m < 4; ++m) _Pragma("unroll") for (int n = 0; n < 2; ++n)
;           stg_w<128>(stg, trow + E_R, tcol + n * 16, pack4(acc[ai][0][m][n] * sig4(acc[ai][1][m][n])));
;         stage_store<128>(stg, (u16*)(ws + OFF_UGLU) + (size_t)brow * 512 + (pn - 2) * 128, 512, tid);
.LBB0_507:
	s_andn2_b64 vcc, exec, s[34:35]
	s_cbranch_vccnz .LBB0_509
	v_mul_f32_e32 v133, 0xbfb8aa3b, v124
	v_exp_f32_e32 v134, v133
	v_mul_f32_e32 v133, 0xbfb8aa3b, v125
	v_exp_f32_e32 v135, v133
	v_mul_f32_e32 v133, 0xbfb8aa3b, v126
	v_exp_f32_e32 v136, v133
	v_mul_f32_e32 v133, 0xbfb8aa3b, v127
	v_pk_add_f32 v[134:135], v[134:135], 1.0 op_sel_hi:[1,0]
	v_exp_f32_e32 v137, v133
	v_lshlrev_b32_e32 v128, 1, v132
	v_lshlrev_b32_e32 v139, 8, v131
	v_and_or_b32 v147, v128, 8, v139
	v_rcp_f32_e32 v135, v135
	v_pk_add_f32 v[136:137], v[136:137], 1.0 op_sel_hi:[1,0]
	v_rcp_f32_e32 v134, v134
	s_nop 0
	v_pk_mul_f32 v[134:135], v[120:121], v[134:135]
	v_rcp_f32_e32 v137, v137
	s_nop 0
	v_cvt_pk_bf16_f32 v134, v134, v135
	v_rcp_f32_e32 v136, v136
	s_nop 0
	v_pk_mul_f32 v[136:137], v[122:123], v[136:137]
	v_mul_f32_e32 v128, 0xbfb8aa3b, v116
	s_nop 0
	v_cvt_pk_bf16_f32 v135, v136, v137
	v_exp_f32_e32 v136, v128
	v_mul_f32_e32 v128, 0xbfb8aa3b, v117
	v_exp_f32_e32 v137, v128
	v_mul_f32_e32 v128, 0xbfb8aa3b, v118
	v_exp_f32_e32 v138, v128
	v_mul_f32_e32 v128, 0xbfb8aa3b, v119
	v_pk_add_f32 v[136:137], v[136:137], 1.0 op_sel_hi:[1,0]
	v_exp_f32_e32 v139, v128
	s_nop 0
	v_pk_add_f32 v[138:139], v[138:139], 1.0 op_sel_hi:[1,0]
	v_lshrrev_b32_e32 v133, 3, v130
	v_xor_b32_e32 v128, v133, v145
	v_rcp_f32_e32 v137, v137
	v_bitop3_b32 v133, v133, v145, 2 bitop3:0x36
	v_rcp_f32_e32 v136, v136
	s_nop 0
	v_pk_mul_f32 v[136:137], v[112:113], v[136:137]
	v_rcp_f32_e32 v139, v139
	s_nop 0
	v_cvt_pk_bf16_f32 v136, v136, v137
	v_rcp_f32_e32 v138, v138
	s_nop 0
	v_pk_mul_f32 v[138:139], v[114:115], v[138:139]
	v_lshl_or_b32 v128, v128, 4, v147
	s_nop 0
	v_cvt_pk_bf16_f32 v137, v138, v139
	v_mul_f32_e32 v138, 0xbfb8aa3b, v108
	v_mul_f32_e32 v139, 0xbfb8aa3b, v109
	v_exp_f32_e32 v138, v138
	v_exp_f32_e32 v139, v139
	v_lshl_or_b32 v133, v133, 4, v147
	v_mul_f32_e32 v148, 0xbfb8aa3b, v110
	v_mul_f32_e32 v149, 0xbfb8aa3b, v111
	v_pk_add_f32 v[138:139], v[138:139], 1.0 op_sel_hi:[1,0]
	v_exp_f32_e32 v148, v148
	v_exp_f32_e32 v149, v149
	s_lshl_b64 s[6:7], s[0:1], 10
	s_add_u32 s5, s26, s6
	v_rcp_f32_e32 v139, v139
	v_pk_add_f32 v[148:149], v[148:149], 1.0 op_sel_hi:[1,0]
	v_rcp_f32_e32 v138, v138
	s_nop 0
	v_pk_mul_f32 v[138:139], v[104:105], v[138:139]
	v_rcp_f32_e32 v149, v149
	s_nop 0
	v_cvt_pk_bf16_f32 v138, v138, v139
	v_mul_f32_e32 v139, 0xbfb8aa3b, v100
	v_exp_f32_e32 v150, v139
	v_mul_f32_e32 v139, 0xbfb8aa3b, v101
	v_exp_f32_e32 v151, v139
	v_rcp_f32_e32 v148, v148
	v_mul_f32_e32 v139, 0xbfb8aa3b, v102
	v_exp_f32_e32 v152, v139
	v_pk_add_f32 v[150:151], v[150:151], 1.0 op_sel_hi:[1,0]
	v_mul_f32_e32 v139, 0xbfb8aa3b, v103
	v_pk_mul_f32 v[148:149], v[106:107], v[148:149]
	v_exp_f32_e32 v153, v139
	s_nop 0
	v_cvt_pk_bf16_f32 v139, v148, v149
	ds_write2st64_b64 v128, v[134:135], v[138:139] offset1:8
	v_rcp_f32_e32 v139, v151
	v_pk_add_f32 v[134:135], v[152:153], 1.0 op_sel_hi:[1,0]
	v_rcp_f32_e32 v138, v150
	s_nop 0
	v_pk_mul_f32 v[138:139], v[96:97], v[138:139]
	v_rcp_f32_e32 v135, v135
	s_nop 0
	v_cvt_pk_bf16_f32 v138, v138, v139
	v_mul_f32_e32 v139, 0xbfb8aa3b, v92
	v_exp_f32_e32 v148, v139
	v_mul_f32_e32 v139, 0xbfb8aa3b, v93
	v_exp_f32_e32 v149, v139
	v_rcp_f32_e32 v134, v134
	v_mul_f32_e32 v139, 0xbfb8aa3b, v94
	v_exp_f32_e32 v150, v139
	v_pk_add_f32 v[148:149], v[148:149], 1.0 op_sel_hi:[1,0]
	v_mul_f32_e32 v139, 0xbfb8aa3b, v95
	v_pk_mul_f32 v[134:135], v[98:99], v[134:135]
	v_exp_f32_e32 v151, v139
	s_nop 0
	v_cvt_pk_bf16_f32 v139, v134, v135
	ds_write2st64_b64 v133, v[136:137], v[138:139] offset1:8
	v_rcp_f32_e32 v137, v149
	v_pk_add_f32 v[134:135], v[150:151], 1.0 op_sel_hi:[1,0]
	v_rcp_f32_e32 v136, v148
	s_nop 0
	v_pk_mul_f32 v[136:137], v[84:85], v[136:137]
	v_rcp_f32_e32 v135, v135
	s_nop 0
	v_cvt_pk_bf16_f32 v136, v136, v137
	v_rcp_f32_e32 v134, v134
	v_mul_f32_e32 v138, 0xbfb8aa3b, v88
	v_mul_f32_e32 v139, 0xbfb8aa3b, v89
	v_exp_f32_e32 v138, v138
	v_exp_f32_e32 v139, v139
	v_mul_f32_e32 v147, 0xbfb8aa3b, v90
	v_exp_f32_e32 v148, v147
	v_mul_f32_e32 v147, 0xbfb8aa3b, v91
	v_pk_add_f32 v[138:139], v[138:139], 1.0 op_sel_hi:[1,0]
	v_exp_f32_e32 v149, v147
	v_pk_mul_f32 v[134:135], v[86:87], v[134:135]
	s_addc_u32 s6, s27, s7
	s_nop 0
	v_cvt_pk_bf16_f32 v137, v134, v135
	v_pk_add_f32 v[134:135], v[148:149], 1.0 op_sel_hi:[1,0]
	v_rcp_f32_e32 v139, v139
	s_add_u32 s4, s5, s4
	v_rcp_f32_e32 v138, v138
	s_nop 0
	v_pk_mul_f32 v[138:139], v[80:81], v[138:139]
	v_rcp_f32_e32 v135, v135
	s_nop 0
	v_cvt_pk_bf16_f32 v138, v138, v139
	v_rcp_f32_e32 v134, v134
	v_mul_f32_e32 v147, 0xbfb8aa3b, v76
	v_exp_f32_e32 v148, v147
	v_mul_f32_e32 v147, 0xbfb8aa3b, v77
	v_exp_f32_e32 v149, v147
	v_mul_f32_e32 v147, 0xbfb8aa3b, v78
	v_exp_f32_e32 v150, v147
	v_mul_f32_e32 v147, 0xbfb8aa3b, v79
	v_pk_add_f32 v[148:149], v[148:149], 1.0 op_sel_hi:[1,0]
	v_exp_f32_e32 v151, v147
	v_pk_mul_f32 v[134:135], v[82:83], v[134:135]
	s_addc_u32 s5, s6, 0
	s_nop 0
	v_cvt_pk_bf16_f32 v139, v134, v135
	v_pk_add_f32 v[134:135], v[150:151], 1.0 op_sel_hi:[1,0]
	v_rcp_f32_e32 v149, v149
	s_add_u32 s4, s4, 0x2f9ffe00
	v_rcp_f32_e32 v148, v148
	s_nop 0
	v_pk_mul_f32 v[148:149], v[60:61], v[148:149]
	v_rcp_f32_e32 v135, v135
	s_nop 0
	v_cvt_pk_bf16_f32 v148, v148, v149
	v_rcp_f32_e32 v134, v134
	v_mul_f32_e32 v147, 0xbfb8aa3b, v64
	v_exp_f32_e32 v150, v147
	v_mul_f32_e32 v147, 0xbfb8aa3b, v65
	v_exp_f32_e32 v151, v147
	v_mul_f32_e32 v147, 0xbfb8aa3b, v66
	v_exp_f32_e32 v152, v147
	v_mul_f32_e32 v147, 0xbfb8aa3b, v67
	v_pk_add_f32 v[150:151], v[150:151], 1.0 op_sel_hi:[1,0]
	v_exp_f32_e32 v153, v147
	v_pk_mul_f32 v[134:135], v[62:63], v[134:135]
	s_addc_u32 s5, s5, 0
	s_nop 0
; __device__ __forceinline__ float bflo(unsigned w) { return __uint_as_float(w << 16); }
; __device__ __forceinline__ float bfhi(unsigned w) { return __uint_as_float(w & 0xffff0000u); }
; __device__ __forceinline__ float sigmoidf_(float x) { return __fdividef(1.f, 1.f + __expf(-x)); }
; __device__ __forceinline__ u32x2 pack4(f32x4 v) { return u32x2{cvtpk(v[0], v[1]), cvtpk(v[2], v[3])}; }
; __device__ __forceinline__ f32x4 unpack4(u32x2 w) { return f32x4{bflo(w[0]), bfhi(w[0]), bflo(w[1]), bfhi(w[1])}; }
; __device__ __forceinline__ f32x4 sig4(f32x4 v) { return f32x4{sigmoidf_(v[0]), sigmoidf_(v[1]), sigmoidf_(v[2]), sigmoidf_(v[3])}; }
; template <int EPI, int nN, int lda, int ldb, int K, int ldc>
; __device__ __forceinline__ void gemm_phase(const Params& p, const u16* __restrict__ A, const u16* __restrict__ Bt, u16* C, u16* shm, int wave_s) {
;     ...
;       } else if (pn < 6) {
;         _Pragma("unroll") for (int ai = 0; ai < 2; ++ai) _Pragma("unroll") for (int m = 0; m < 4; ++m) _Pragma("unroll") for (int n = 0; n < 2; ++n)
;           stg_w<128>(stg, trow + E_R, tcol + n * 16, pack4(acc[ai][0][m][n] * sig4(acc[ai][1][m][n])));
;         stage_store<128>(stg, (u16*)(ws + OFF_UGLU) + (size_t)brow * 512 + (pn - 2) * 128, 512, tid);
	v_cvt_pk_bf16_f32 v149, v134, v135
	ds_write2st64_b64 v128, v[136:137], v[148:149] offset0:16 offset1:24
	v_rcp_f32_e32 v137, v151
	v_pk_add_f32 v[134:135], v[152:153], 1.0 op_sel_hi:[1,0]
	v_rcp_f32_e32 v136, v150
	s_nop 0
	v_pk_mul_f32 v[136:137], v[48:49], v[136:137]
	v_rcp_f32_e32 v135, v135
	s_nop 0
	v_cvt_pk_bf16_f32 v136, v136, v137
	v_mul_f32_e32 v137, 0xbfb8aa3b, v68
	v_exp_f32_e32 v148, v137
	v_mul_f32_e32 v137, 0xbfb8aa3b, v69
	v_exp_f32_e32 v149, v137
	v_rcp_f32_e32 v134, v134
	v_mul_f32_e32 v137, 0xbfb8aa3b, v70
	v_exp_f32_e32 v150, v137
	v_pk_add_f32 v[148:149], v[148:149], 1.0 op_sel_hi:[1,0]
	v_mul_f32_e32 v137, 0xbfb8aa3b, v71
	v_pk_mul_f32 v[134:135], v[50:51], v[134:135]
	v_exp_f32_e32 v151, v137
	s_nop 0
	v_cvt_pk_bf16_f32 v137, v134, v135
	ds_write2st64_b64 v133, v[138:139], v[136:137] offset0:16 offset1:24
	v_rcp_f32_e32 v137, v149
	v_pk_add_f32 v[134:135], v[150:151], 1.0 op_sel_hi:[1,0]
	v_rcp_f32_e32 v136, v148
	s_nop 0
	v_pk_mul_f32 v[136:137], v[72:73], v[136:137]
	v_rcp_f32_e32 v135, v135
	s_nop 0
	v_cvt_pk_bf16_f32 v136, v136, v137
	v_rcp_f32_e32 v134, v134
	v_mul_f32_e32 v138, 0xbfb8aa3b, v52
	v_mul_f32_e32 v139, 0xbfb8aa3b, v53
	v_exp_f32_e32 v138, v138
	v_exp_f32_e32 v139, v139
	v_mul_f32_e32 v147, 0xbfb8aa3b, v54
	v_exp_f32_e32 v148, v147
	v_mul_f32_e32 v147, 0xbfb8aa3b, v55
	v_pk_add_f32 v[138:139], v[138:139], 1.0 op_sel_hi:[1,0]
	v_exp_f32_e32 v149, v147
	v_pk_mul_f32 v[134:135], v[74:75], v[134:135]
	s_nop 0
	s_nop 0
	v_cvt_pk_bf16_f32 v137, v134, v135
	v_pk_add_f32 v[134:135], v[148:149], 1.0 op_sel_hi:[1,0]
	v_rcp_f32_e32 v139, v139
	v_rcp_f32_e32 v138, v138
	s_nop 0
	v_pk_mul_f32 v[138:139], v[56:57], v[138:139]
	v_rcp_f32_e32 v135, v135
	s_nop 0
	v_cvt_pk_bf16_f32 v138, v138, v139
	v_rcp_f32_e32 v134, v134
	v_mul_f32_e32 v147, 0xbfb8aa3b, v40
	v_exp_f32_e32 v148, v147
	v_mul_f32_e32 v147, 0xbfb8aa3b, v41
	v_exp_f32_e32 v149, v147
	v_mul_f32_e32 v147, 0xbfb8aa3b, v42
	v_exp_f32_e32 v150, v147
	v_mul_f32_e32 v147, 0xbfb8aa3b, v43
	v_pk_add_f32 v[148:149], v[148:149], 1.0 op_sel_hi:[1,0]
	v_exp_f32_e32 v151, v147
	v_pk_mul_f32 v[134:135], v[58:59], v[134:135]
	s_nop 0
	s_nop 0
	v_cvt_pk_bf16_f32 v139, v134, v135
	v_pk_add_f32 v[134:135], v[150:151], 1.0 op_sel_hi:[1,0]
	v_rcp_f32_e32 v149, v149
	v_rcp_f32_e32 v148, v148
	s_nop 0
	v_pk_mul_f32 v[148:149], v[44:45], v[148:149]
	v_rcp_f32_e32 v135, v135
	s_nop 0
	v_cvt_pk_bf16_f32 v148, v148, v149
	v_rcp_f32_e32 v134, v134
	v_mul_f32_e32 v147, 0xbfb8aa3b, v32
	v_exp_f32_e32 v150, v147
	v_mul_f32_e32 v147, 0xbfb8aa3b, v33
	v_exp_f32_e32 v151, v147
	v_mul_f32_e32 v147, 0xbfb8aa3b, v34
	v_exp_f32_e32 v152, v147
	v_mul_f32_e32 v147, 0xbfb8aa3b, v35
	v_pk_add_f32 v[150:151], v[150:151], 1.0 op_sel_hi:[1,0]
	v_exp_f32_e32 v153, v147
	v_pk_mul_f32 v[134:135], v[46:47], v[134:135]
	s_nop 0
	s_nop 0
	v_cvt_pk_bf16_f32 v149, v134, v135
	ds_write2st64_b64 v128, v[136:137], v[148:149] offset0:64 offset1:72
	v_rcp_f32_e32 v137, v151
	v_pk_add_f32 v[134:135], v[152:153], 1.0 op_sel_hi:[1,0]
	v_rcp_f32_e32 v136, v150
	s_nop 0
	v_pk_mul_f32 v[136:137], v[36:37], v[136:137]
	v_rcp_f32_e32 v135, v135
	s_nop 0
	v_cvt_pk_bf16_f32 v136, v136, v137
	v_mul_f32_e32 v137, 0xbfb8aa3b, v24
	v_exp_f32_e32 v148, v137
	v_mul_f32_e32 v137, 0xbfb8aa3b, v25
	v_exp_f32_e32 v149, v137
	v_rcp_f32_e32 v134, v134
	v_mul_f32_e32 v137, 0xbfb8aa3b, v26
	v_exp_f32_e32 v150, v137
	v_pk_add_f32 v[148:149], v[148:149], 1.0 op_sel_hi:[1,0]
	v_mul_f32_e32 v137, 0xbfb8aa3b, v27
	v_pk_mul_f32 v[134:135], v[38:39], v[134:135]
	v_exp_f32_e32 v151, v137
	s_nop 0
	v_cvt_pk_bf16_f32 v137, v134, v135
	ds_write2st64_b64 v133, v[138:139], v[136:137] offset0:64 offset1:72
	v_rcp_f32_e32 v137, v149
	v_pk_add_f32 v[134:135], v[150:151], 1.0 op_sel_hi:[1,0]
	v_rcp_f32_e32 v136, v148
	s_nop 0
	v_pk_mul_f32 v[136:137], v[28:29], v[136:137]
	v_rcp_f32_e32 v135, v135
	s_nop 0
	v_cvt_pk_bf16_f32 v136, v136, v137
	v_rcp_f32_e32 v134, v134
	v_mul_f32_e32 v138, 0xbfb8aa3b, v16
	v_mul_f32_e32 v139, 0xbfb8aa3b, v17
	v_exp_f32_e32 v138, v138
	v_exp_f32_e32 v139, v139
	v_mul_f32_e32 v147, 0xbfb8aa3b, v18
	v_exp_f32_e32 v148, v147
	v_mul_f32_e32 v147, 0xbfb8aa3b, v19
	v_pk_add_f32 v[138:139], v[138:139], 1.0 op_sel_hi:[1,0]
	v_exp_f32_e32 v149, v147
	v_pk_mul_f32 v[134:135], v[30:31], v[134:135]
	s_nop 0
	s_nop 0
	v_cvt_pk_bf16_f32 v137, v134, v135
	v_pk_add_f32 v[134:135], v[148:149], 1.0 op_sel_hi:[1,0]
	v_rcp_f32_e32 v139, v139
	v_rcp_f32_e32 v138, v138
	s_nop 0
	v_pk_mul_f32 v[138:139], v[20:21], v[138:139]
	v_rcp_f32_e32 v135, v135
	s_nop 0
	v_cvt_pk_bf16_f32 v138, v138, v139
	v_rcp_f32_e32 v134, v134
	v_mul_f32_e32 v147, 0xbfb8aa3b, v8
	v_exp_f32_e32 v148, v147
	v_mul_f32_e32 v147, 0xbfb8aa3b, v9
	v_exp_f32_e32 v149, v147
	v_mul_f32_e32 v147, 0xbfb8aa3b, v10
	v_exp_f32_e32 v150, v147
	v_mul_f32_e32 v147, 0xbfb8aa3b, v11
	v_pk_add_f32 v[148:149], v[148:149], 1.0 op_sel_hi:[1,0]
	v_exp_f32_e32 v151, v147
	v_pk_mul_f32 v[134:135], v[22:23], v[134:135]
	s_nop 0
	s_nop 0
	v_cvt_pk_bf16_f32 v139, v134, v135
	v_pk_add_f32 v[134:135], v[150:151], 1.0 op_sel_hi:[1,0]
	v_rcp_f32_e32 v149, v149
	v_rcp_f32_e32 v148, v148
	s_nop 0
	v_pk_mul_f32 v[148:149], v[12:13], v[148:149]
	v_rcp_f32_e32 v135, v135
	s_nop 0
	v_cvt_pk_bf16_f32 v148, v148, v149
	v_rcp_f32_e32 v134, v134
	v_mul_f32_e32 v147, 0xbfb8aa3b, v0
	v_exp_f32_e32 v150, v147
	v_mul_f32_e32 v147, 0xbfb8aa3b, v1
	v_exp_f32_e32 v151, v147
	v_mul_f32_e32 v147, 0xbfb8aa3b, v2
	v_exp_f32_e32 v152, v147
	v_mul_f32_e32 v147, 0xbfb8aa3b, v3
	v_pk_add_f32 v[150:151], v[150:151], 1.0 op_sel_hi:[1,0]
	v_exp_f32_e32 v153, v147
	v_div_scale_f32 v147, s[34:35], v151, v151, 1.0
	v_rcp_f32_e32 v154, v147
	v_pk_mul_f32 v[134:135], v[14:15], v[134:135]
	s_nop 0
	s_nop 0
	v_cvt_pk_bf16_f32 v149, v134, v135
	ds_write2st64_b64 v128, v[136:137], v[148:149] offset0:80 offset1:88
	v_fma_f32 v128, -v147, v154, 1.0
	v_fmac_f32_e32 v154, v128, v154
	v_rcp_f32_e32 v137, v151
	v_pk_add_f32 v[134:135], v[152:153], 1.0 op_sel_hi:[1,0]
	v_rcp_f32_e32 v136, v150
	s_nop 0
	v_pk_mul_f32 v[136:137], v[4:5], v[136:137]
	v_div_scale_f32 v147, s[34:35], v134, v134, 1.0
	v_rcp_f32_e32 v150, v147
	v_rcp_f32_e32 v135, v135
	s_nop 0
	v_cvt_pk_bf16_f32 v136, v136, v137
	v_fma_f32 v128, -v147, v150, 1.0
	v_fmac_f32_e32 v150, v128, v150
	v_div_scale_f32 v128, vcc, 1.0, v134, 1.0
	v_mul_f32_e32 v148, v128, v150
	v_fma_f32 v149, -v147, v148, v128
	v_fmac_f32_e32 v148, v149, v150
	v_rcp_f32_e32 v134, v134
	v_lshrrev_b32_e32 v128, 28, v146
	v_add_u32_e32 v128, v144, v128
	v_pk_mul_f32 v[134:135], v[6:7], v[134:135]
	s_nop 0
	s_nop 0
	v_cvt_pk_bf16_f32 v137, v134, v135
	ds_write2st64_b64 v133, v[138:139], v[136:137] offset0:80 offset1:88
	v_ashrrev_i32_e32 v133, 4, v128
	v_xor_b32_e32 v128, v133, v143
	v_lshlrev_b32_e32 v128, 4, v128
	v_and_b32_e32 v150, 0xf0, v128
	v_lshlrev_b32_e32 v128, 3, v143
	v_and_b32_e32 v151, 0x78, v128
	v_lshl_or_b32 v128, v133, 8, v150
	v_add_u32_e32 v152, 32, v133
	s_waitcnt vmcnt(0) lgkmcnt(0)
	s_barrier
; template <int NC> __device__ __forceinline__ void stage_store(const char* stg, u16* dst, int ld, int tid) {
;   constexpr int CH = NC / 8, RPI = 512 / CH;
;   __syncthreads();
;   const int j = tid & (CH - 1), r0 = tid / CH;
; #pragma unroll
;   for (int i = 0; i < 256 / RPI; ++i) { const int r = i * RPI + r0;
;     __builtin_nontemporal_store(stg_r<NC>(stg, r, j), reinterpret_cast<u32x4*>(dst + (unsigned)(r * ld + j * 8))); }
;   __syncthreads();
; }
	ds_read_b128 v[134:137], v128
	v_lshl_or_b32 v138, v152, 8, v150
	ds_read_b128 v[146:149], v138
	v_lshl_or_b32 v128, v133, 9, v151
	v_lshl_add_u64 v[138:139], v[128:129], 1, s[4:5]
	v_lshl_or_b32 v128, v152, 9, v151
	s_waitcnt lgkmcnt(1)
	global_store_dwordx4 v[138:139], v[134:137], off nt
	v_add_u32_e32 v152, 0x60, v133
	v_lshl_or_b32 v138, v152, 8, v150
	v_lshl_add_u64 v[134:135], v[128:129], 1, s[4:5]
	v_add_u32_e32 v128, 64, v133
	s_waitcnt lgkmcnt(0)
	global_store_dwordx4 v[134:135], v[146:149], off nt
	v_lshl_or_b32 v134, v128, 8, v150
	ds_read_b128 v[134:137], v134
	ds_read_b128 v[146:149], v138
	v_lshl_or_b32 v128, v128, 9, v151
	v_lshl_add_u64 v[138:139], v[128:129], 1, s[4:5]
	v_lshl_or_b32 v128, v152, 9, v151
	s_waitcnt lgkmcnt(1)
	global_store_dwordx4 v[138:139], v[134:137], off nt
	v_add_u32_e32 v152, 0xa0, v133
	v_lshl_or_b32 v138, v152, 8, v150
	v_lshl_add_u64 v[134:135], v[128:129], 1, s[4:5]
	v_add_u32_e32 v128, 0x80, v133
	s_waitcnt lgkmcnt(0)
	global_store_dwordx4 v[134:135], v[146:149], off nt
	v_lshl_or_b32 v134, v128, 8, v150
	ds_read_b128 v[134:137], v134
	ds_read_b128 v[146:149], v138
	v_lshl_or_b32 v128, v128, 9, v151
	v_lshl_add_u64 v[138:139], v[128:129], 1, s[4:5]
	v_lshl_or_b32 v128, v152, 9, v151
	s_waitcnt lgkmcnt(1)
	global_store_dwordx4 v[138:139], v[134:137], off nt
	s_nop 1
	v_lshl_add_u64 v[134:135], v[128:129], 1, s[4:5]
	v_add_u32_e32 v128, 0xc0, v133
	s_waitcnt lgkmcnt(0)
	global_store_dwordx4 v[134:135], v[146:149], off nt
	v_lshl_or_b32 v134, v128, 8, v150
	v_add_u32_e32 v133, 0xe0, v133
	ds_read_b128 v[134:137], v134
	v_lshl_or_b32 v138, v133, 8, v150
	ds_read_b128 v[146:149], v138
	v_lshl_or_b32 v128, v128, 9, v151
	v_lshl_add_u64 v[138:139], v[128:129], 1, s[4:5]
	v_lshl_or_b32 v128, v133, 9, v151
	s_waitcnt lgkmcnt(1)
	global_store_dwordx4 v[138:139], v[134:137], off nt
	s_nop 1
	v_lshl_add_u64 v[134:135], v[128:129], 1, s[4:5]
	s_waitcnt lgkmcnt(0)
	global_store_dwordx4 v[134:135], v[146:149], off nt
	s_barrier

; __device__ __forceinline__ float sigmoidf_(float x) { return __fdividef(1.f, 1.f + __expf(-x)); }
; __device__ void phase2(const Params& p, char* smem, int wave_s) {
;     ...
;     for (int tt = 0; tt < 4; ++tt) {
;       const int tok = wid * 4 + tt;
;       const float* r = cv + tok * 512 + lane * 8;
;       const f32x4 a = *reinterpret_cast<const f32x4*>(r), b2 = *reinterpret_cast<const f32x4*>(r + 4);
;       float x[8] = {a[0], a[1], a[2], a[3], b2[0], b2[1], b2[2], b2[3]};
;       float sm = 0.f;
; #pragma unroll
;       for (int e = 0; e < 8; ++e) sm += x[e];
;       const float mu = wave_sum(sm) * (1.f / 512.f);
;       float d2 = 0.f;
; #pragma unroll
;       for (int e = 0; e < 8; ++e) { x[e] -= mu; d2 += x[e] * x[e]; }
;       const float rs = rsqrtf(wave_sum(d2) * (1.f / 512.f) + EPS);
;       float y[8];
; #pragma unroll
;       for (int e = 0; e < 8; ++e) { const float t_ = x[e] * rs * gl8[e] + bl8[e]; y[e] = t_ * sigmoidf_(t_); }
;       __builtin_nontemporal_store(u32x4{cvtpk(y[0], y[1]), cvtpk(y[2], y[3]), cvtpk(y[4], y[5]), cvtpk(y[6], y[7])},
;                                   reinterpret_cast<u32x4*>(u2 + (base + t0 + tok) * 512 + lane * 8));
.LBB0_580:
	ds_read_b128 v[126:129], v210 offset:63488
	ds_read_b128 v[130:133], v210 offset:63504
	s_ashr_i32 s20, s42, 6
	s_ashr_i32 s21, s20, 31
	s_lshl_b64 s[42:43], s[20:21], 11
	s_waitcnt lgkmcnt(1)
	v_add_f32_e32 v45, 0, v126
	v_add_f32_e32 v45, v127, v45
	v_add_f32_e32 v45, v128, v45
	v_add_f32_e32 v45, v129, v45
	s_waitcnt lgkmcnt(0)
	v_add_f32_e32 v45, v130, v45
	v_add_f32_e32 v45, v131, v45
	v_add_f32_e32 v45, v132, v45
	v_add_f32_e32 v45, v133, v45
	v_mov_b32_e32 v134, v45
	s_or_b32 s42, s42, s47
	s_addk_i32 s56, 0x2000
	s_waitcnt lgkmcnt(0)
	s_nop 1
	v_permlane32_swap_b32_e32 v45, v134
	v_add_f32_e32 v45, v45, v134
	ds_bpermute_b32 v134, v204, v45
	s_waitcnt lgkmcnt(0)
	v_add_f32_e32 v45, v45, v134
	s_waitcnt lgkmcnt(0)
	s_nop 1
	v_add_f32_dpp v45, v45, v45 row_mirror row_mask:0xf bank_mask:0xf
	s_waitcnt lgkmcnt(0)
	s_nop 1
	v_add_f32_dpp v45, v45, v45 row_half_mirror row_mask:0xf bank_mask:0xf
	s_waitcnt lgkmcnt(0)
	s_nop 1
	v_add_f32_dpp v45, v45, v45 quad_perm:[2,3,0,1] row_mask:0xf bank_mask:0xf
	s_waitcnt lgkmcnt(0)
	s_nop 1
	v_add_f32_dpp v45, v45, v45 quad_perm:[1,0,3,2] row_mask:0xf bank_mask:0xf
	v_fmamk_f32 v137, v45, 0xbb000000, v127
	v_mul_f32_e32 v134, 0x3b000000, v45
	v_fmamk_f32 v136, v45, 0xbb000000, v126
	v_fmamk_f32 v128, v45, 0xbb000000, v128
	v_fmac_f32_e32 v129, 0xbb000000, v45
	v_mul_f32_e32 v45, v137, v137
	v_fmac_f32_e32 v45, v136, v136
	v_pk_add_f32 v[130:131], v[130:131], v[134:135] op_sel_hi:[1,0] neg_lo:[0,1] neg_hi:[0,1]
	v_fmac_f32_e32 v45, v128, v128
	v_pk_add_f32 v[126:127], v[132:133], v[134:135] op_sel_hi:[1,0] neg_lo:[0,1] neg_hi:[0,1]
	v_pk_mul_f32 v[132:133], v[130:131], v[130:131]
	v_fmac_f32_e32 v45, v129, v129
	v_add_f32_e32 v45, v132, v45
	v_pk_mul_f32 v[134:135], v[126:127], v[126:127]
	v_add_f32_e32 v45, v133, v45
	v_add_f32_e32 v45, v134, v45
	v_add_f32_e32 v45, v135, v45
	v_mov_b32_e32 v132, v45
	s_waitcnt lgkmcnt(0)
	s_nop 1
	v_permlane32_swap_b32_e32 v45, v132
	v_add_f32_e32 v45, v45, v132
	ds_bpermute_b32 v132, v204, v45
	s_waitcnt lgkmcnt(0)
	v_add_f32_e32 v45, v45, v132
	s_waitcnt lgkmcnt(0)
	s_nop 1
	v_add_f32_dpp v45, v45, v45 row_mirror row_mask:0xf bank_mask:0xf
	s_waitcnt lgkmcnt(0)
	s_nop 1
	v_add_f32_dpp v45, v45, v45 row_half_mirror row_mask:0xf bank_mask:0xf
	s_waitcnt lgkmcnt(0)
	s_nop 1
	v_add_f32_dpp v45, v45, v45 quad_perm:[2,3,0,1] row_mask:0xf bank_mask:0xf
	s_waitcnt lgkmcnt(0)
	s_nop 1
	v_add_f32_dpp v45, v45, v45 quad_perm:[1,0,3,2] row_mask:0xf bank_mask:0xf
	v_fmamk_f32 v45, v45, 0x3b000000, v211
	v_mul_f32_e32 v132, 0x4b800000, v45
	v_cmp_gt_f32_e32 vcc, s45, v45
	s_nop 1
	v_cndmask_b32_e32 v45, v45, v132, vcc
	v_rsq_f32_e32 v45, v45
	s_nop 0
	v_mul_f32_e32 v132, 0x45800000, v45
	v_cndmask_b32_e32 v45, v45, v132, vcc
	v_mul_f32_e32 v132, v136, v45
	v_mul_f32_e32 v133, v137, v45
	s_waitcnt vmcnt(0)
	v_fma_f32 v132, v8, v132, v12
	v_fma_f32 v133, v9, v133, v13
	v_mul_f32_e32 v134, 0xbfb8aa3b, v132
	v_mul_f32_e32 v135, 0xbfb8aa3b, v133
	v_exp_f32_e32 v134, v134
	v_mul_f32_e32 v128, v128, v45
	v_exp_f32_e32 v135, v135
	v_fma_f32 v128, v10, v128, v14
	v_mul_f32_e32 v136, 0xbfb8aa3b, v128
	v_exp_f32_e32 v136, v136
	v_add_f32_e32 v134, 1.0, v134
	v_add_f32_e32 v135, 1.0, v135
	v_add_f32_e32 v136, 1.0, v136
	v_mul_f32_e32 v129, v129, v45
	v_div_scale_f32 v142, s[22:23], v136, v136, 1.0
	v_fma_f32 v129, v11, v129, v15
	v_rcp_f32_e32 v147, v142
	v_mul_f32_e32 v137, 0xbfb8aa3b, v129
	v_exp_f32_e32 v137, v137
	v_fma_f32 v151, -v142, v147, 1.0
	v_div_scale_f32 v143, s[22:23], 1.0, v136, 1.0
	v_fmac_f32_e32 v147, v151, v147
	v_add_f32_e32 v137, 1.0, v137
	v_mul_f32_e32 v151, v143, v147
	s_mov_b64 vcc, s[20:21]
	v_fma_f32 v154, -v142, v151, v143
	v_rcp_f32_e32 v134, v134
	s_nop 0
	v_mul_f32_e32 v139, v132, v134
	v_rcp_f32_e32 v132, v135
	v_mul_f32_e32 v130, v130, v45
	v_mul_f32_e32 v138, v133, v132
	s_mov_b64 vcc, s[22:23]
	v_fma_f32 v133, v0, v130, v4
	v_mul_f32_e32 v130, 0xbfb8aa3b, v133
	v_rcp_f32_e32 v132, v136
	v_exp_f32_e32 v130, v130
	v_mul_f32_e32 v140, v128, v132
	v_add_f32_e32 v130, 1.0, v130
	v_mul_f32_e32 v131, v131, v45
	v_fma_f32 v136, v1, v131, v5
	v_rcp_f32_e32 v128, v137
	v_mul_f32_e32 v131, 0xbfb8aa3b, v136
	v_mul_f32_e32 v141, v129, v128
	v_exp_f32_e32 v131, v131
	s_nop 0
	v_add_f32_e32 v137, 1.0, v131
	v_rcp_f32_e32 v132, v130
	ds_read_b128 v[128:131], v212 offset:63488
	v_mul_f32_e32 v144, v133, v132
	ds_read_b128 v[132:135], v212 offset:63504
	s_waitcnt lgkmcnt(1)
	v_add_f32_e32 v145, 0, v128
	v_add_f32_e32 v145, v129, v145
	v_add_f32_e32 v145, v130, v145
	v_add_f32_e32 v145, v131, v145
	s_waitcnt lgkmcnt(0)
	v_add_f32_e32 v145, v132, v145
	v_add_f32_e32 v145, v133, v145
	v_add_f32_e32 v145, v134, v145
	v_add_f32_e32 v145, v135, v145
	v_mov_b32_e32 v146, v145
	s_waitcnt lgkmcnt(0)
	s_nop 1
	v_permlane32_swap_b32_e32 v145, v146
	v_add_f32_e32 v145, v145, v146
	ds_bpermute_b32 v146, v204, v145
	v_mul_f32_e32 v126, v126, v45
	v_fma_f32 v147, v2, v126, v6
	s_waitcnt lgkmcnt(0)
	v_add_f32_e32 v126, v145, v146
	v_mul_f32_e32 v146, 0xbfb8aa3b, v147
	v_exp_f32_e32 v146, v146
	v_rcp_f32_e32 v137, v137
	s_waitcnt lgkmcnt(0)
	s_nop 1
	v_add_f32_dpp v126, v126, v126 row_mirror row_mask:0xf bank_mask:0xf
	v_add_f32_e32 v145, 1.0, v146
	s_waitcnt lgkmcnt(0)
	s_nop 1
	v_add_f32_dpp v126, v126, v126 row_half_mirror row_mask:0xf bank_mask:0xf
	v_mul_f32_e32 v142, v136, v137
	v_mul_f32_e32 v45, v127, v45
	s_waitcnt lgkmcnt(0)
	s_nop 1
	v_add_f32_dpp v126, v126, v126 quad_perm:[2,3,0,1] row_mask:0xf bank_mask:0xf
	v_fma_f32 v45, v3, v45, v7
	s_waitcnt lgkmcnt(0)
; __device__ __forceinline__ float sigmoidf_(float x) { return __fdividef(1.f, 1.f + __expf(-x)); }
; __device__ void phase2(const Params& p, char* smem, int wave_s) {
;     ...
;     for (int tt = 0; tt < 4; ++tt) {
;       const int tok = wid * 4 + tt;
;       const float* r = cv + tok * 512 + lane * 8;
;       const f32x4 a = *reinterpret_cast<const f32x4*>(r), b2 = *reinterpret_cast<const f32x4*>(r + 4);
;       float x[8] = {a[0], a[1], a[2], a[3], b2[0], b2[1], b2[2], b2[3]};
;       float sm = 0.f;
; #pragma unroll
;       for (int e = 0; e < 8; ++e) sm += x[e];
;       const float mu = wave_sum(sm) * (1.f / 512.f);
;       float d2 = 0.f;
; #pragma unroll
;       for (int e = 0; e < 8; ++e) { x[e] -= mu; d2 += x[e] * x[e]; }
;       const float rs = rsqrtf(wave_sum(d2) * (1.f / 512.f) + EPS);
;       float y[8];
; #pragma unroll
;       for (int e = 0; e < 8; ++e) { const float t_ = x[e] * rs * gl8[e] + bl8[e]; y[e] = t_ * sigmoidf_(t_); }
;       __builtin_nontemporal_store(u32x4{cvtpk(y[0], y[1]), cvtpk(y[2], y[3]), cvtpk(y[4], y[5]), cvtpk(y[6], y[7])},
;                                   reinterpret_cast<u32x4*>(u2 + (base + t0 + tok) * 512 + lane * 8));
	s_nop 1
	v_add_f32_dpp v136, v126, v126 quad_perm:[1,0,3,2] row_mask:0xf bank_mask:0xf
	v_fmamk_f32 v152, v136, 0xbb000000, v129
	v_fmamk_f32 v151, v136, 0xbb000000, v128
	v_mul_f32_e32 v153, v152, v152
	v_mul_f32_e32 v126, 0x3b000000, v136
	v_fmac_f32_e32 v153, v151, v151
	v_fmamk_f32 v130, v136, 0xbb000000, v130
	v_fmac_f32_e32 v153, v130, v130
	v_fmac_f32_e32 v131, 0xbb000000, v136
	v_pk_add_f32 v[136:137], v[132:133], v[126:127] op_sel_hi:[1,0] neg_lo:[0,1] neg_hi:[0,1]
	v_fmac_f32_e32 v153, v131, v131
	v_pk_mul_f32 v[128:129], v[136:137], v[136:137]
	v_add_f32_e32 v128, v128, v153
	v_add_f32_e32 v153, v129, v128
	v_pk_add_f32 v[128:129], v[134:135], v[126:127] op_sel_hi:[1,0] neg_lo:[0,1] neg_hi:[0,1]
	v_pk_mul_f32 v[132:133], v[128:129], v[128:129]
	s_nop 0
	v_add_f32_e32 v126, v132, v153
	v_add_f32_e32 v126, v133, v126
	v_mov_b32_e32 v132, v126
	v_rcp_f32_e32 v133, v145
	s_nop 0
	v_mul_f32_e32 v143, v147, v133
	s_waitcnt lgkmcnt(0)
	s_nop 1
	v_permlane32_swap_b32_e32 v126, v132
	v_add_f32_e32 v126, v126, v132
	ds_bpermute_b32 v127, v204, v126
	v_mul_f32_e32 v132, 0xbfb8aa3b, v45
	v_exp_f32_e32 v132, v132
	s_waitcnt lgkmcnt(0)
	v_add_f32_e32 v126, v126, v127
	v_add_f32_e32 v132, 1.0, v132
	s_waitcnt lgkmcnt(0)
	s_nop 1
	v_add_f32_dpp v126, v126, v126 row_mirror row_mask:0xf bank_mask:0xf
	s_waitcnt lgkmcnt(0)
	s_nop 1
	v_add_f32_dpp v126, v126, v126 row_half_mirror row_mask:0xf bank_mask:0xf
	s_waitcnt lgkmcnt(0)
	s_nop 1
	v_add_f32_dpp v126, v126, v126 quad_perm:[2,3,0,1] row_mask:0xf bank_mask:0xf
	v_rcp_f32_e32 v132, v132
	s_nop 0
	v_mul_f32_e32 v45, v45, v132
	s_nop 0
	v_cvt_pk_bf16_f32 v132, v139, v138
	s_waitcnt lgkmcnt(0)
	s_nop 1
	v_add_f32_dpp v126, v126, v126 quad_perm:[1,0,3,2] row_mask:0xf bank_mask:0xf
	v_fmamk_f32 v126, v126, 0x3b000000, v211
	v_mul_f32_e32 v127, 0x4b800000, v126
	v_cmp_gt_f32_e32 vcc, s45, v126
	s_nop 0
	v_cvt_pk_bf16_f32 v133, v140, v141
	s_nop 0
	v_cvt_pk_bf16_f32 v135, v143, v45
	s_nop 0
	v_cvt_pk_bf16_f32 v134, v144, v142
	s_nop 1
	v_cndmask_b32_e32 v126, v126, v127, vcc
	v_rsq_f32_e32 v126, v126
	s_nop 0
	v_mul_f32_e32 v127, 0x45800000, v126
	v_cndmask_b32_e32 v138, v126, v127, vcc
	v_mul_f32_e32 v126, v151, v138
	v_fma_f32 v139, v8, v126, v12
	v_mul_f32_e32 v126, 0xbfb8aa3b, v139
	v_exp_f32_e32 v140, v126
	v_lshl_add_u64 v[126:127], s[42:43], 0, v[116:117]
	v_lshlrev_b64 v[126:127], 10, v[126:127]
	v_lshl_add_u64 v[126:127], v[118:119], 0, v[126:127]
	v_add_f32_e32 v45, 1.0, v140
	global_store_dwordx4 v[126:127], v[132:135], off nt
	v_mul_f32_e32 v130, v130, v138
	v_fma_f32 v130, v10, v130, v14
	v_mul_f32_e32 v132, v152, v138
	v_fma_f32 v132, v9, v132, v13
	v_mul_f32_e32 v133, 0xbfb8aa3b, v132
	v_exp_f32_e32 v133, v133
	s_nop 0
	v_add_f32_e32 v133, 1.0, v133
	v_rcp_f32_e32 v45, v45
	s_nop 0
	v_mul_f32_e32 v45, v139, v45
	v_mul_f32_e32 v139, 0xbfb8aa3b, v130
	v_exp_f32_e32 v139, v139
	s_nop 0
	v_add_f32_e32 v134, 1.0, v139
	v_mul_f32_e32 v131, v131, v138
	v_rcp_f32_e32 v126, v133
	v_fma_f32 v131, v11, v131, v15
	v_mul_f32_e32 v141, v132, v126
	v_mul_f32_e32 v132, 0xbfb8aa3b, v131
	v_exp_f32_e32 v132, v132
	s_nop 0
	v_add_f32_e32 v132, 1.0, v132
	v_rcp_f32_e32 v126, v134
	s_nop 0
	v_mul_f32_e32 v139, v130, v126
	v_mul_f32_e32 v130, v136, v138
	v_fma_f32 v134, v0, v130, v4
	v_mul_f32_e32 v130, 0xbfb8aa3b, v134
	v_exp_f32_e32 v130, v130
	s_nop 0
	v_add_f32_e32 v130, 1.0, v130
	v_rcp_f32_e32 v126, v132
	s_nop 0
	v_mul_f32_e32 v140, v131, v126
	v_mul_f32_e32 v131, v137, v138
	v_fma_f32 v142, v1, v131, v5
	v_mul_f32_e32 v131, 0xbfb8aa3b, v142
	v_exp_f32_e32 v131, v131
	v_rcp_f32_e32 v126, v130
	v_add_f32_e32 v127, 1.0, v131
	ds_read_b128 v[130:133], v213 offset:63488
	v_mul_f32_e32 v145, v134, v126
	ds_read_b128 v[134:137], v213 offset:63504
	s_waitcnt lgkmcnt(1)
	v_add_f32_e32 v126, 0, v130
	v_add_f32_e32 v126, v131, v126
	v_add_f32_e32 v126, v132, v126
	v_add_f32_e32 v126, v133, v126
	s_waitcnt lgkmcnt(0)
	v_add_f32_e32 v126, v134, v126
	v_add_f32_e32 v126, v135, v126
	v_add_f32_e32 v126, v136, v126
	v_add_f32_e32 v126, v137, v126
	v_mov_b32_e32 v146, v126
	s_waitcnt lgkmcnt(0)
	s_nop 1
	v_permlane32_swap_b32_e32 v126, v146
	v_add_f32_e32 v126, v126, v146
	ds_bpermute_b32 v146, v204, v126
	v_mul_f32_e32 v128, v128, v138
	v_fma_f32 v128, v2, v128, v6
	s_waitcnt lgkmcnt(0)
	v_add_f32_e32 v126, v126, v146
	v_mul_f32_e32 v147, 0xbfb8aa3b, v128
	v_exp_f32_e32 v147, v147
	v_rcp_f32_e32 v127, v127
	s_waitcnt lgkmcnt(0)
	s_nop 1
	v_add_f32_dpp v126, v126, v126 row_mirror row_mask:0xf bank_mask:0xf
	v_add_f32_e32 v146, 1.0, v147
	s_waitcnt lgkmcnt(0)
	s_nop 1
	v_add_f32_dpp v126, v126, v126 row_half_mirror row_mask:0xf bank_mask:0xf
	v_mul_f32_e32 v142, v142, v127
	v_mul_f32_e32 v129, v129, v138
	s_waitcnt lgkmcnt(0)
	s_nop 1
	v_add_f32_dpp v126, v126, v126 quad_perm:[2,3,0,1] row_mask:0xf bank_mask:0xf
	v_fma_f32 v129, v3, v129, v7
	s_waitcnt lgkmcnt(0)
	s_nop 1
	v_add_f32_dpp v127, v126, v126 quad_perm:[1,0,3,2] row_mask:0xf bank_mask:0xf
	v_fmamk_f32 v151, v127, 0xbb000000, v131
	v_fmamk_f32 v150, v127, 0xbb000000, v130
	v_mul_f32_e32 v152, v151, v151
	v_mul_f32_e32 v126, 0x3b000000, v127
	v_fmac_f32_e32 v152, v150, v150
	v_fmamk_f32 v132, v127, 0xbb000000, v132
	v_fmac_f32_e32 v152, v132, v132
	v_fmac_f32_e32 v133, 0xbb000000, v127
	v_pk_add_f32 v[134:135], v[134:135], v[126:127] op_sel_hi:[1,0] neg_lo:[0,1] neg_hi:[0,1]
	v_fmac_f32_e32 v152, v133, v133
	v_pk_mul_f32 v[130:131], v[134:135], v[134:135]
	v_add_f32_e32 v127, v130, v152
	v_add_f32_e32 v152, v131, v127
	v_pk_add_f32 v[126:127], v[136:137], v[126:127] op_sel_hi:[1,0] neg_lo:[0,1] neg_hi:[0,1]
	v_mul_f32_e32 v137, 0xbfb8aa3b, v129
	v_pk_mul_f32 v[130:131], v[126:127], v[126:127]
	v_exp_f32_e32 v137, v137
	v_add_f32_e32 v130, v130, v152
	v_add_f32_e32 v130, v131, v130
	v_mov_b32_e32 v131, v130
	v_add_f32_e32 v137, 1.0, v137
	s_waitcnt lgkmcnt(0)
; __device__ __forceinline__ float sigmoidf_(float x) { return __fdividef(1.f, 1.f + __expf(-x)); }
; __device__ void phase2(const Params& p, char* smem, int wave_s) {
;     ...
;     for (int tt = 0; tt < 4; ++tt) {
;       const int tok = wid * 4 + tt;
;       const float* r = cv + tok * 512 + lane * 8;
;       const f32x4 a = *reinterpret_cast<const f32x4*>(r), b2 = *reinterpret_cast<const f32x4*>(r + 4);
;       float x[8] = {a[0], a[1], a[2], a[3], b2[0], b2[1], b2[2], b2[3]};
;       float sm = 0.f;
; #pragma unroll
;       for (int e = 0; e < 8; ++e) sm += x[e];
;       const float mu = wave_sum(sm) * (1.f / 512.f);
;       float d2 = 0.f;
; #pragma unroll
;       for (int e = 0; e < 8; ++e) { x[e] -= mu; d2 += x[e] * x[e]; }
;       const float rs = rsqrtf(wave_sum(d2) * (1.f / 512.f) + EPS);
;       float y[8];
; #pragma unroll
;       for (int e = 0; e < 8; ++e) { const float t_ = x[e] * rs * gl8[e] + bl8[e]; y[e] = t_ * sigmoidf_(t_); }
;       __builtin_nontemporal_store(u32x4{cvtpk(y[0], y[1]), cvtpk(y[2], y[3]), cvtpk(y[4], y[5]), cvtpk(y[6], y[7])},
;                                   reinterpret_cast<u32x4*>(u2 + (base + t0 + tok) * 512 + lane * 8));
	s_nop 1
	v_permlane32_swap_b32_e32 v130, v131
	v_add_f32_e32 v130, v130, v131
	ds_bpermute_b32 v131, v204, v130
	v_rcp_f32_e32 v136, v146
	s_waitcnt lgkmcnt(0)
	v_add_f32_e32 v130, v130, v131
	v_mul_f32_e32 v136, v128, v136
	s_waitcnt lgkmcnt(0)
	s_nop 1
	v_add_f32_dpp v130, v130, v130 row_mirror row_mask:0xf bank_mask:0xf
	s_waitcnt lgkmcnt(0)
	s_nop 1
	v_add_f32_dpp v128, v130, v130 row_half_mirror row_mask:0xf bank_mask:0xf
	s_waitcnt lgkmcnt(0)
	s_nop 1
	v_add_f32_dpp v128, v128, v128 quad_perm:[2,3,0,1] row_mask:0xf bank_mask:0xf
	v_rcp_f32_e32 v131, v137
	s_waitcnt lgkmcnt(0)
	s_nop 1
	v_add_f32_dpp v128, v128, v128 quad_perm:[1,0,3,2] row_mask:0xf bank_mask:0xf
	v_fmamk_f32 v128, v128, 0x3b000000, v211
	v_mul_f32_e32 v130, 0x4b800000, v128
	v_cmp_gt_f32_e32 vcc, s45, v128
	v_mul_f32_e32 v131, v129, v131
	s_nop 0
	v_cvt_pk_bf16_f32 v129, v139, v140
	s_nop 0
	v_cvt_pk_bf16_f32 v131, v136, v131
	v_lshl_add_u64 v[136:137], s[42:43], 0, v[120:121]
	v_cndmask_b32_e32 v128, v128, v130, vcc
	v_rsq_f32_e32 v130, v128
	s_nop 0
	v_cvt_pk_bf16_f32 v128, v45, v141
	v_lshlrev_b64 v[136:137], 10, v[136:137]
	v_lshl_add_u64 v[136:137], v[118:119], 0, v[136:137]
	v_mul_f32_e32 v45, 0x45800000, v130
	v_cndmask_b32_e32 v45, v130, v45, vcc
	v_mul_f32_e32 v130, v150, v45
	v_fma_f32 v138, v8, v130, v12
	v_mul_f32_e32 v130, 0xbfb8aa3b, v138
	v_exp_f32_e32 v139, v130
	s_nop 0
	v_cvt_pk_bf16_f32 v130, v145, v142
	global_store_dwordx4 v[136:137], v[128:131], off nt
	v_mul_f32_e32 v132, v132, v45
	v_add_f32_e32 v139, 1.0, v139
	v_mul_f32_e32 v130, v151, v45
	v_fma_f32 v130, v9, v130, v13
	v_mul_f32_e32 v131, 0xbfb8aa3b, v130
	v_exp_f32_e32 v131, v131
	s_nop 0
	v_add_f32_e32 v131, 1.0, v131
	v_rcp_f32_e32 v128, v139
	v_fma_f32 v132, v10, v132, v14
	v_mul_f32_e32 v138, v138, v128
	v_mul_f32_e32 v139, 0xbfb8aa3b, v132
	v_exp_f32_e32 v139, v139
	s_nop 0
	v_add_f32_e32 v136, 1.0, v139
	v_rcp_f32_e32 v128, v131
	s_nop 0
	v_mul_f32_e32 v137, v130, v128
	v_mul_f32_e32 v130, v133, v45
	v_fma_f32 v130, v11, v130, v15
	v_mul_f32_e32 v131, 0xbfb8aa3b, v130
	v_exp_f32_e32 v131, v131
	s_nop 0
	v_add_f32_e32 v131, 1.0, v131
	v_rcp_f32_e32 v128, v136
	s_nop 0
	v_mul_f32_e32 v136, v132, v128
	v_mul_f32_e32 v132, v134, v45
	v_fma_f32 v132, v0, v132, v4
	v_mul_f32_e32 v134, 0xbfb8aa3b, v132
	v_exp_f32_e32 v134, v134
	s_nop 0
	v_add_f32_e32 v133, 1.0, v134
	v_rcp_f32_e32 v128, v131
	s_nop 0
	v_mul_f32_e32 v139, v130, v128
	v_mul_f32_e32 v130, v135, v45
	v_fma_f32 v141, v1, v130, v5
	v_mul_f32_e32 v130, 0xbfb8aa3b, v141
	v_exp_f32_e32 v130, v130
	v_rcp_f32_e32 v133, v133
	v_add_f32_e32 v140, 1.0, v130
	ds_read_b128 v[128:131], v214 offset:63488
	v_mul_f32_e32 v144, v132, v133
	ds_read_b128 v[132:135], v214 offset:63504
	s_waitcnt lgkmcnt(1)
	v_add_f32_e32 v145, 0, v128
	v_add_f32_e32 v145, v129, v145
	v_add_f32_e32 v145, v130, v145
	v_add_f32_e32 v145, v131, v145
	s_waitcnt lgkmcnt(0)
	v_add_f32_e32 v145, v132, v145
	v_add_f32_e32 v145, v133, v145
	v_add_f32_e32 v145, v134, v145
	v_add_f32_e32 v145, v135, v145
	v_mov_b32_e32 v146, v145
	v_mul_f32_e32 v126, v126, v45
	s_waitcnt lgkmcnt(0)
	s_nop 1
	v_permlane32_swap_b32_e32 v145, v146
	v_add_f32_e32 v145, v145, v146
	ds_bpermute_b32 v146, v204, v145
	v_fma_f32 v147, v2, v126, v6
	v_rcp_f32_e32 v140, v140
	s_waitcnt lgkmcnt(0)
	v_add_f32_e32 v126, v145, v146
	v_mul_f32_e32 v146, 0xbfb8aa3b, v147
	v_exp_f32_e32 v146, v146
	v_mul_f32_e32 v140, v141, v140
	v_mul_f32_e32 v45, v127, v45
	s_waitcnt lgkmcnt(0)
	s_nop 1
	v_add_f32_dpp v126, v126, v126 row_mirror row_mask:0xf bank_mask:0xf
	v_add_f32_e32 v145, 1.0, v146
	v_div_scale_f32 v146, s[20:21], v145, v145, 1.0
	v_rcp_f32_e32 v148, v146
	s_waitcnt lgkmcnt(0)
	s_nop 1
	v_add_f32_dpp v126, v126, v126 row_half_mirror row_mask:0xf bank_mask:0xf
	v_fma_f32 v45, v3, v45, v7
	v_fma_f32 v141, -v146, v148, 1.0
	v_fmac_f32_e32 v148, v141, v148
	v_div_scale_f32 v142, vcc, 1.0, v145, 1.0
	s_waitcnt lgkmcnt(0)
	s_nop 1
	v_add_f32_dpp v126, v126, v126 quad_perm:[2,3,0,1] row_mask:0xf bank_mask:0xf
	v_mul_f32_e32 v143, v142, v148
	v_fma_f32 v149, -v146, v143, v142
	s_waitcnt lgkmcnt(0)
	s_nop 1
	v_add_f32_dpp v141, v126, v126 quad_perm:[1,0,3,2] row_mask:0xf bank_mask:0xf
	v_fmamk_f32 v151, v141, 0xbb000000, v129
	v_fmamk_f32 v150, v141, 0xbb000000, v128
	v_mul_f32_e32 v152, v151, v151
	v_mul_f32_e32 v126, 0x3b000000, v141
	v_fmac_f32_e32 v152, v150, v150
	v_fmamk_f32 v130, v141, 0xbb000000, v130
	v_fmac_f32_e32 v152, v130, v130
	v_fmac_f32_e32 v131, 0xbb000000, v141
	v_pk_add_f32 v[132:133], v[132:133], v[126:127] op_sel_hi:[1,0] neg_lo:[0,1] neg_hi:[0,1]
	v_fmac_f32_e32 v152, v131, v131
	v_pk_mul_f32 v[128:129], v[132:133], v[132:133]
	v_pk_add_f32 v[134:135], v[134:135], v[126:127] op_sel_hi:[1,0] neg_lo:[0,1] neg_hi:[0,1]
	v_add_f32_e32 v128, v128, v152
	v_add_f32_e32 v141, v129, v128
	v_pk_mul_f32 v[128:129], v[134:135], v[134:135]
	s_nop 0
	v_add_f32_e32 v126, v128, v141
	v_add_f32_e32 v126, v129, v126
	v_mov_b32_e32 v128, v126
	v_rcp_f32_e32 v129, v145
	s_nop 0
	v_mul_f32_e32 v129, v147, v129
	s_waitcnt lgkmcnt(0)
; __device__ __forceinline__ float sigmoidf_(float x) { return __fdividef(1.f, 1.f + __expf(-x)); }
; __device__ void phase2(const Params& p, char* smem, int wave_s) {
;     ...
;     for (int tt = 0; tt < 4; ++tt) {
;       const int tok = wid * 4 + tt;
;       const float* r = cv + tok * 512 + lane * 8;
;       const f32x4 a = *reinterpret_cast<const f32x4*>(r), b2 = *reinterpret_cast<const f32x4*>(r + 4);
;       float x[8] = {a[0], a[1], a[2], a[3], b2[0], b2[1], b2[2], b2[3]};
;       float sm = 0.f;
; #pragma unroll
;       for (int e = 0; e < 8; ++e) sm += x[e];
;       const float mu = wave_sum(sm) * (1.f / 512.f);
;       float d2 = 0.f;
; #pragma unroll
;       for (int e = 0; e < 8; ++e) { x[e] -= mu; d2 += x[e] * x[e]; }
;       const float rs = rsqrtf(wave_sum(d2) * (1.f / 512.f) + EPS);
;       float y[8];
; #pragma unroll
;       for (int e = 0; e < 8; ++e) { const float t_ = x[e] * rs * gl8[e] + bl8[e]; y[e] = t_ * sigmoidf_(t_); }
;       __builtin_nontemporal_store(u32x4{cvtpk(y[0], y[1]), cvtpk(y[2], y[3]), cvtpk(y[4], y[5]), cvtpk(y[6], y[7])},
;                                   reinterpret_cast<u32x4*>(u2 + (base + t0 + tok) * 512 + lane * 8));
;     }
;   }
	s_nop 1
	v_permlane32_swap_b32_e32 v126, v128
	v_add_f32_e32 v126, v126, v128
	ds_bpermute_b32 v127, v204, v126
	v_mul_f32_e32 v128, 0xbfb8aa3b, v45
	v_exp_f32_e32 v128, v128
	s_waitcnt lgkmcnt(0)
	v_add_f32_e32 v126, v126, v127
	v_add_f32_e32 v128, 1.0, v128
	v_div_scale_f32 v141, s[20:21], v128, v128, 1.0
	v_rcp_f32_e32 v142, v141
	s_waitcnt lgkmcnt(0)
	s_nop 1
	v_add_f32_dpp v126, v126, v126 row_mirror row_mask:0xf bank_mask:0xf
	v_fma_f32 v143, -v141, v142, 1.0
	v_fmac_f32_e32 v142, v143, v142
	v_div_scale_f32 v143, vcc, 1.0, v128, 1.0
	s_waitcnt lgkmcnt(0)
	s_nop 1
	v_add_f32_dpp v126, v126, v126 row_half_mirror row_mask:0xf bank_mask:0xf
	v_mul_f32_e32 v145, v143, v142
	v_fma_f32 v146, -v141, v145, v143
	v_fmac_f32_e32 v145, v146, v142
	s_waitcnt lgkmcnt(0)
	s_nop 1
	v_add_f32_dpp v126, v126, v126 quad_perm:[2,3,0,1] row_mask:0xf bank_mask:0xf
	v_rcp_f32_e32 v128, v128
	s_nop 0
	v_mul_f32_e32 v45, v45, v128
	s_nop 0
	v_cvt_pk_bf16_f32 v129, v129, v45
	s_waitcnt lgkmcnt(0)
	s_nop 1
	v_add_f32_dpp v126, v126, v126 quad_perm:[1,0,3,2] row_mask:0xf bank_mask:0xf
	v_fmamk_f32 v126, v126, 0x3b000000, v211
	v_mul_f32_e32 v127, 0x4b800000, v126
	v_cmp_gt_f32_e32 vcc, s45, v126
	s_nop 1
	v_cndmask_b32_e32 v126, v126, v127, vcc
	v_rsq_f32_e32 v141, v126
	s_nop 0
	v_cvt_pk_bf16_f32 v126, v138, v137
	s_nop 0
	v_cvt_pk_bf16_f32 v127, v136, v139
	v_lshl_add_u64 v[136:137], s[42:43], 0, v[122:123]
	v_mul_f32_e32 v128, 0x45800000, v141
	v_cndmask_b32_e32 v138, v141, v128, vcc
	v_mul_f32_e32 v128, v150, v138
	v_fma_f32 v139, v8, v128, v12
	v_mul_f32_e32 v128, 0xbfb8aa3b, v139
	v_exp_f32_e32 v141, v128
	v_lshlrev_b64 v[136:137], 10, v[136:137]
	s_nop 0
	v_cvt_pk_bf16_f32 v128, v144, v140
	v_lshl_add_u64 v[136:137], v[118:119], 0, v[136:137]
	v_add_f32_e32 v45, 1.0, v141
	v_div_scale_f32 v140, s[20:21], v45, v45, 1.0
	v_rcp_f32_e32 v141, v140
	global_store_dwordx4 v[136:137], v[126:129], off nt
	v_mul_f32_e32 v130, v130, v138
	v_fma_f32 v130, v10, v130, v14
	v_mul_f32_e32 v128, v151, v138
	v_fma_f32 v128, v9, v128, v13
	v_mul_f32_e32 v129, 0xbfb8aa3b, v128
	v_exp_f32_e32 v129, v129
	v_fma_f32 v126, -v140, v141, 1.0
	v_fmac_f32_e32 v141, v126, v141
	v_add_f32_e32 v129, 1.0, v129
	v_rcp_f32_e32 v45, v45
	s_nop 0
	v_mul_f32_e32 v45, v139, v45
	v_mul_f32_e32 v139, 0xbfb8aa3b, v130
	v_exp_f32_e32 v139, v139
	s_nop 0
	v_add_f32_e32 v136, 1.0, v139
	v_rcp_f32_e32 v126, v129
	v_mul_f32_e32 v129, v131, v138
	v_fma_f32 v129, v11, v129, v15
	v_mul_f32_e32 v131, 0xbfb8aa3b, v129
	v_exp_f32_e32 v131, v131
	v_mul_f32_e32 v126, v128, v126
	v_add_f32_e32 v131, 1.0, v131
	v_mul_f32_e32 v132, v132, v138
	v_fma_f32 v132, v0, v132, v4
	v_rcp_f32_e32 v127, v136
	v_mul_f32_e32 v136, 0xbfb8aa3b, v132
	v_exp_f32_e32 v136, v136
	v_mul_f32_e32 v127, v130, v127
	v_add_f32_e32 v136, 1.0, v136
	v_rcp_f32_e32 v128, v131
	v_mul_f32_e32 v131, v133, v138
	v_fma_f32 v131, v1, v131, v5
	v_mul_f32_e32 v133, 0xbfb8aa3b, v131
	v_mul_f32_e32 v128, v129, v128
	v_exp_f32_e32 v133, v133
	s_nop 0
	v_add_f32_e32 v133, 1.0, v133
	v_div_scale_f32 v137, s[20:21], v133, v133, 1.0
	v_rcp_f32_e32 v139, v137
	v_mul_f32_e32 v134, v134, v138
	v_fma_f32 v134, v2, v134, v6
	v_rcp_f32_e32 v129, v136
	v_mul_f32_e32 v136, 0xbfb8aa3b, v134
	v_fma_f32 v130, -v137, v139, 1.0
	v_exp_f32_e32 v136, v136
	v_fmac_f32_e32 v139, v130, v139
	v_mul_f32_e32 v129, v132, v129
	v_add_f32_e32 v136, 1.0, v136
	v_div_scale_f32 v137, s[20:21], v136, v136, 1.0
	v_rcp_f32_e32 v140, v137
	v_rcp_f32_e32 v130, v133
	v_mul_f32_e32 v133, v135, v138
	v_fma_f32 v133, v3, v133, v7
	v_mul_f32_e32 v135, 0xbfb8aa3b, v133
	v_mul_f32_e32 v130, v131, v130
	v_fma_f32 v131, -v137, v140, 1.0
	v_exp_f32_e32 v135, v135
	v_fmac_f32_e32 v140, v131, v140
	v_add_f32_e32 v135, 1.0, v135
	v_div_scale_f32 v137, s[20:21], v135, v135, 1.0
	v_rcp_f32_e32 v138, v137
	v_rcp_f32_e32 v131, v136
	s_nop 0
	v_mul_f32_e32 v131, v134, v131
	v_fma_f32 v132, -v137, v138, 1.0
	v_fmac_f32_e32 v138, v132, v138
	v_div_scale_f32 v132, vcc, 1.0, v135, 1.0
	v_mul_f32_e32 v134, v132, v138
	v_fma_f32 v136, -v137, v134, v132
	v_fmac_f32_e32 v134, v136, v138
	v_rcp_f32_e32 v132, v135
	s_nop 0
	v_mul_f32_e32 v132, v133, v132
	s_nop 0
	v_cvt_pk_bf16_f32 v127, v127, v128
	s_nop 0
	v_cvt_pk_bf16_f32 v128, v129, v130
	s_nop 0
	v_cvt_pk_bf16_f32 v129, v131, v132
	v_lshl_add_u64 v[130:131], s[42:43], 0, v[124:125]
	v_lshlrev_b64 v[130:131], 10, v[130:131]
	v_lshl_add_u64 v[130:131], v[118:119], 0, v[130:131]
	s_andn2_b64 vcc, exec, s[40:41]
	s_mov_b32 s42, s46
	s_nop 0
	v_cvt_pk_bf16_f32 v126, v45, v126
	global_store_dwordx4 v[130:131], v[126:129], off nt
	s_cbranch_vccz .LBB0_616
